# in-proj (ret, diff) and gate/up GEMMs: first K-iteration peeled with srcC=0 MFMAs, 128-register accumulator zeroing per tile removed
# baseline (speedup 1.0000x reference)
; #define PG8_STAGE(bufoff, gbase, voff) do { _Pragma("unroll") for (int _i = 0; _i < 2; ++_i) \
;         __builtin_amdgcn_global_load_lds((const unsigned*)((const char*)(gbase) + (voff)[_i]), (PG8_LAS unsigned*)(lds + (bufoff) + ldsw + _i * 8192), 16, 0, 0); } while (0)
; #define PG8_LDA(dst, b, h) do { _Pragma("unroll") for (int m = 0; m < 4; ++m) _Pragma("unroll") for (int k = 0; k < 2; ++k) dst[m][k] = *(const PG8_LAS bf16x8*)(lds + PG8_SA(b, h) + aoff + m * 2048 + k * 1024); } while (0)
; #define PG8_LDB(dst, b, h) do { _Pragma("unroll") for (int n = 0; n < 2; ++n) _Pragma("unroll") for (int k = 0; k < 2; ++k) dst[n][k] = *(const PG8_LAS bf16x8*)(lds + PG8_SB(b, h) + boff + n * 2048 + k * 1024); } while (0)
; #define PG8_WAIT_V(n) asm volatile("s_waitcnt vmcnt(" #n ")" ::: "memory")
; #define PG8_WAIT_L(n) asm volatile("s_waitcnt lgkmcnt(" #n ")" ::: "memory")
; #define PG8_BAR __builtin_amdgcn_s_barrier()
; #define PG8_SCHED __builtin_amdgcn_sched_barrier(0)
; template <class Epi, class Sched, bool ALIGN_EPI = false, bool SP2 = false>
; __device__ __forceinline__ void gemm_phase(PG8_LAS unsigned char* lds, const Gemm g, const Sched& S, const Epi& E) {
;     ...
;         const bool has_next = S.next(ui + 1, nxt);
;         const char* nA = has_next ? (const char*)g.A + (size_t)nxt.pm * tstep : cA; const char* nB = has_next ? (const char*)g.Bt + (size_t)nxt.pn * tstep : cB;
;         for (int t = 0; t < nt; t += 2) {
;             const bool last = (t == nt - 2);
;             const char* a1 = cA + (size_t)(t + 1) * kstep;
;             const char* a2 = last ? nA : cA + (size_t)(t + 2) * kstep; const char* b2 = last ? nB : cB + (size_t)(t + 2) * kstep;
;             const char* a3 = a2 + kstep; const char* b3 = b2 + kstep;
;             if (last && has_next) S.a_ready(nxt);
;             if constexpr (SP2) {
;             PG8_LDB(B0, 0, 0); PG8_LDB(B1, 0, 1); PG8_SCHED; PG8_LDA(At, 0, 0); PG8_STAGE(PG8_SA(1, 1), a1 + hstep, voffA);
;             PG8_WAIT_V(8); PG8_WAIT_L(0); PG8_BAR; PG8_MMA(0, 0, At, B0); PG8_MMA(0, 1, At, B1); PG8_BAR; PG8_SCHED;
;             PG8_LDA(At, 0, 1); PG8_STAGE(PG8_SB(0, 0), b2, voffB); PG8_STAGE(PG8_SB(0, 1), b2 + hstep, voffB); PG8_STAGE(PG8_SA(0, 0), a2, voffA);
;             PG8_WAIT_V(8); PG8_WAIT_L(0); PG8_BAR; PG8_MMA(1, 0, At, B0); PG8_MMA(1, 1, At, B1); PG8_BAR; PG8_SCHED;
.LBB0_144:
	s_ashr_i32 s31, s30, 31
	s_lshl_b64 s[34:35], s[30:31], 19
	s_add_u32 s34, s5, s34
	s_addc_u32 s35, s18, s35
	s_and_b64 s[36:37], s[40:41], exec
	s_cselect_b32 s31, s35, s91
	s_cselect_b32 s43, s34, s90
	s_ashr_i32 s29, s28, 31
	s_lshl_b64 s[36:37], s[28:29], 19
	s_add_u32 s36, s19, s36
	s_addc_u32 s37, s44, s37
	s_and_b64 s[46:47], s[40:41], exec
	s_cselect_b32 s29, s37, s51
	s_cselect_b32 s62, s36, s50
	s_add_u32 s90, s90, 0x40080
	s_addc_u32 s91, s91, 0
	s_add_u32 s63, s50, 0x100
	s_addc_u32 s64, s51, 0
	s_mov_b32 s65, -2
	s_add_u32 s46, s90, 0xfffc0080
	s_addc_u32 s47, s91, -1
	s_add_i32 s66, 0, 0x10000
	s_cmp_eq_u32 s65, 12
	s_cselect_b32 s51, s31, s47
	s_cselect_b32 s50, s43, s46
	v_add_u32_e32 v142, s66, v145
	s_cselect_b32 s47, s29, s64
	s_cselect_b32 s46, s62, s63
	s_add_i32 s68, 0, 0x14000
	ds_read_b128 v[150:153], v142
	ds_read_b128 v[154:157], v142 offset:1024
	ds_read_b128 v[158:161], v142 offset:2048
	ds_read_b128 v[162:165], v142 offset:3072
	v_add_u32_e32 v142, s68, v145
	ds_read_b128 v[166:169], v142
	ds_read_b128 v[170:173], v142 offset:1024
	ds_read_b128 v[174:177], v142 offset:2048
	ds_read_b128 v[178:181], v142 offset:3072
	v_lshl_add_u64 v[142:143], s[90:91], 0, v[138:139]
	s_add_i32 m0, s52, 0xc000
	ds_read_b128 v[182:185], v149
	ds_read_b128 v[186:189], v149 offset:1024
	ds_read_b128 v[190:193], v149 offset:2048
	ds_read_b128 v[204:207], v149 offset:3072
	ds_read_b128 v[208:211], v149 offset:4096
	ds_read_b128 v[212:215], v149 offset:5120
	ds_read_b128 v[216:219], v149 offset:6144
	ds_read_b128 v[220:223], v149 offset:7168
	global_load_lds_dwordx4 v[142:143], off
	v_lshl_add_u64 v[142:143], s[90:91], 0, v[140:141]
	s_add_i32 m0, s52, 0xe000
	s_nop 0
	global_load_lds_dwordx4 v[142:143], off
	s_waitcnt vmcnt(8)
	s_waitcnt lgkmcnt(0)
	s_barrier
	s_setprio 1
	s_waitcnt lgkmcnt(0)
	v_mfma_f32_16x16x32_bf16 v[126:129], v[150:153], v[182:185], 0
	v_mfma_f32_16x16x32_bf16 v[122:125], v[158:161], v[182:185], 0
	v_mfma_f32_16x16x32_bf16 v[114:117], v[150:153], v[190:193], 0
	v_mfma_f32_16x16x32_bf16 v[106:109], v[158:161], v[190:193], 0
	v_mfma_f32_16x16x32_bf16 v[98:101], v[150:153], v[208:211], 0
	v_mfma_f32_16x16x32_bf16 v[90:93], v[158:161], v[208:211], 0
	v_mfma_f32_16x16x32_bf16 v[82:85], v[150:153], v[216:219], 0
	v_mfma_f32_16x16x32_bf16 v[74:77], v[158:161], v[216:219], 0
	v_mfma_f32_16x16x32_bf16 v[126:129], v[154:157], v[186:189], v[126:129]
	v_mfma_f32_16x16x32_bf16 v[122:125], v[162:165], v[186:189], v[122:125]
	v_mfma_f32_16x16x32_bf16 v[114:117], v[154:157], v[204:207], v[114:117]
	v_mfma_f32_16x16x32_bf16 v[106:109], v[162:165], v[204:207], v[106:109]
	v_mfma_f32_16x16x32_bf16 v[98:101], v[154:157], v[212:215], v[98:101]
	v_mfma_f32_16x16x32_bf16 v[90:93], v[162:165], v[212:215], v[90:93]
	v_mfma_f32_16x16x32_bf16 v[82:85], v[154:157], v[220:223], v[82:85]
	v_mfma_f32_16x16x32_bf16 v[74:77], v[162:165], v[220:223], v[74:77]
	s_setprio 0
	s_setprio 1
	v_mfma_f32_16x16x32_bf16 v[118:121], v[166:169], v[182:185], 0
	v_mfma_f32_16x16x32_bf16 v[110:113], v[174:177], v[182:185], 0
	v_mfma_f32_16x16x32_bf16 v[102:105], v[166:169], v[190:193], 0
	v_mfma_f32_16x16x32_bf16 v[94:97], v[174:177], v[190:193], 0
	v_mfma_f32_16x16x32_bf16 v[86:89], v[166:169], v[208:211], 0
	v_mfma_f32_16x16x32_bf16 v[78:81], v[174:177], v[208:211], 0
	v_mfma_f32_16x16x32_bf16 v[70:73], v[166:169], v[216:219], 0
	v_mfma_f32_16x16x32_bf16 v[66:69], v[174:177], v[216:219], 0
	v_mfma_f32_16x16x32_bf16 v[118:121], v[170:173], v[186:189], v[118:121]
	v_mfma_f32_16x16x32_bf16 v[110:113], v[178:181], v[186:189], v[110:113]
	v_mfma_f32_16x16x32_bf16 v[102:105], v[170:173], v[204:207], v[102:105]
	v_mfma_f32_16x16x32_bf16 v[94:97], v[178:181], v[204:207], v[94:97]
	v_mfma_f32_16x16x32_bf16 v[86:89], v[170:173], v[212:215], v[86:89]
	v_mfma_f32_16x16x32_bf16 v[78:81], v[178:181], v[212:215], v[78:81]
	v_mfma_f32_16x16x32_bf16 v[70:73], v[170:173], v[220:223], v[70:73]
	v_mfma_f32_16x16x32_bf16 v[66:69], v[178:181], v[220:223], v[66:69]
	s_setprio 0
	s_barrier
	s_add_i32 s66, s66, s45
	v_lshl_add_u64 v[142:143], s[46:47], 0, v[134:135]
	s_mov_b32 m0, s66
	ds_read_b128 v[182:185], v149 offset:16384
	ds_read_b128 v[186:189], v149 offset:17408
	ds_read_b128 v[190:193], v149 offset:18432
	ds_read_b128 v[204:207], v149 offset:19456
	ds_read_b128 v[208:211], v149 offset:20480
	ds_read_b128 v[212:215], v149 offset:21504
	ds_read_b128 v[216:219], v149 offset:22528
	ds_read_b128 v[220:223], v149 offset:23552
	global_load_lds_dwordx4 v[142:143], off
	s_add_i32 m0, s66, 0x2000
	s_add_u32 s66, s46, 0x40000
	v_lshl_add_u64 v[146:147], s[46:47], 0, v[130:131]
	s_addc_u32 s67, s47, 0
	s_add_i32 s68, s68, s45
	global_load_lds_dwordx4 v[146:147], off
	v_lshl_add_u64 v[224:225], s[66:67], 0, v[134:135]
	s_mov_b32 m0, s68
	v_lshl_add_u64 v[226:227], s[50:51], 0, v[132:133]
	global_load_lds_dwordx4 v[224:225], off
	v_lshl_add_u64 v[224:225], s[66:67], 0, v[130:131]
	s_add_i32 m0, s68, 0x2000
	s_nop 0
	global_load_lds_dwordx4 v[224:225], off
	v_lshl_add_u64 v[224:225], s[50:51], 0, v[136:137]
	s_mov_b32 m0, s52
	s_nop 0
	global_load_lds_dwordx4 v[224:225], off
	s_mov_b32 m0, s53
	s_nop 0
	global_load_lds_dwordx4 v[226:227], off
	s_waitcnt vmcnt(8)
	s_waitcnt lgkmcnt(0)
	s_barrier
; #define PG8_STAGE(bufoff, gbase, voff) do { _Pragma("unroll") for (int _i = 0; _i < 2; ++_i) \
;         __builtin_amdgcn_global_load_lds((const unsigned*)((const char*)(gbase) + (voff)[_i]), (PG8_LAS unsigned*)(lds + (bufoff) + ldsw + _i * 8192), 16, 0, 0); } while (0)
; #define PG8_LDA(dst, b, h) do { _Pragma("unroll") for (int m = 0; m < 4; ++m) _Pragma("unroll") for (int k = 0; k < 2; ++k) dst[m][k] = *(const PG8_LAS bf16x8*)(lds + PG8_SA(b, h) + aoff + m * 2048 + k * 1024); } while (0)
; #define PG8_LDB(dst, b, h) do { _Pragma("unroll") for (int n = 0; n < 2; ++n) _Pragma("unroll") for (int k = 0; k < 2; ++k) dst[n][k] = *(const PG8_LAS bf16x8*)(lds + PG8_SB(b, h) + boff + n * 2048 + k * 1024); } while (0)
; #define PG8_MMA(ai, bj, At, Bt) do { __builtin_amdgcn_s_setprio(1); _Pragma("unroll") for (int m = 0; m < 4; ++m) _Pragma("unroll") for (int n = 0; n < 2; ++n) _Pragma("unroll") for (int k = 0; k < 2; ++k) \
;         acc[ai][bj][m][n] = __builtin_amdgcn_mfma_f32_16x16x32_bf16(Bt[n][k], At[m][k], acc[ai][bj][m][n], 0, 0, 0); __builtin_amdgcn_s_setprio(0); } while (0)
; #define PG8_WAIT_V(n) asm volatile("s_waitcnt vmcnt(" #n ")" ::: "memory")
; #define PG8_WAIT_L(n) asm volatile("s_waitcnt lgkmcnt(" #n ")" ::: "memory")
; #define PG8_BAR __builtin_amdgcn_s_barrier()
; #define PG8_SCHED __builtin_amdgcn_sched_barrier(0)
; template <class Epi, class Sched, bool ALIGN_EPI = false, bool SP2 = false>
; __device__ __forceinline__ void gemm_phase(PG8_LAS unsigned char* lds, const Gemm g, const Sched& S, const Epi& E) {
;     ...
;             PG8_WAIT_V(8); PG8_WAIT_L(0); PG8_BAR; PG8_MMA(0, 0, At, B0); PG8_MMA(0, 1, At, B1); PG8_BAR; PG8_SCHED;
;             PG8_LDA(At, 0, 1); PG8_STAGE(PG8_SB(0, 0), b2, voffB); PG8_STAGE(PG8_SB(0, 1), b2 + hstep, voffB); PG8_STAGE(PG8_SA(0, 0), a2, voffA);
;             PG8_WAIT_V(8); PG8_WAIT_L(0); PG8_BAR; PG8_MMA(1, 0, At, B0); PG8_MMA(1, 1, At, B1); PG8_BAR; PG8_SCHED;
;             PG8_LDB(B0, 1, 0); PG8_LDB(B1, 1, 1); PG8_SCHED; PG8_LDA(At, 1, 0); PG8_STAGE(PG8_SA(0, 1), a2 + hstep, voffA);
;             PG8_WAIT_V(8); PG8_WAIT_L(0); PG8_BAR; PG8_MMA(0, 0, At, B0); PG8_MMA(0, 1, At, B1); PG8_BAR; PG8_SCHED;
	s_setprio 1
	s_waitcnt lgkmcnt(0)
	v_mfma_f32_16x16x32_bf16 v[62:65], v[150:153], v[182:185], 0
	v_mfma_f32_16x16x32_bf16 v[58:61], v[158:161], v[182:185], 0
	v_mfma_f32_16x16x32_bf16 v[50:53], v[150:153], v[190:193], 0
	v_mfma_f32_16x16x32_bf16 v[42:45], v[158:161], v[190:193], 0
	v_mfma_f32_16x16x32_bf16 v[34:37], v[150:153], v[208:211], 0
	v_mfma_f32_16x16x32_bf16 v[24:27], v[158:161], v[208:211], 0
	v_mfma_f32_16x16x32_bf16 v[16:19], v[150:153], v[216:219], 0
	v_mfma_f32_16x16x32_bf16 v[8:11], v[158:161], v[216:219], 0
	v_mfma_f32_16x16x32_bf16 v[62:65], v[154:157], v[186:189], v[62:65]
	v_mfma_f32_16x16x32_bf16 v[58:61], v[162:165], v[186:189], v[58:61]
	v_mfma_f32_16x16x32_bf16 v[50:53], v[154:157], v[204:207], v[50:53]
	v_mfma_f32_16x16x32_bf16 v[42:45], v[162:165], v[204:207], v[42:45]
	v_mfma_f32_16x16x32_bf16 v[34:37], v[154:157], v[212:215], v[34:37]
	v_mfma_f32_16x16x32_bf16 v[24:27], v[162:165], v[212:215], v[24:27]
	v_mfma_f32_16x16x32_bf16 v[16:19], v[154:157], v[220:223], v[16:19]
	v_mfma_f32_16x16x32_bf16 v[8:11], v[162:165], v[220:223], v[8:11]
	s_setprio 0
	s_setprio 1
	v_mfma_f32_16x16x32_bf16 v[54:57], v[166:169], v[182:185], 0
	v_mfma_f32_16x16x32_bf16 v[46:49], v[174:177], v[182:185], 0
	v_mfma_f32_16x16x32_bf16 v[38:41], v[166:169], v[190:193], 0
	v_mfma_f32_16x16x32_bf16 v[28:31], v[174:177], v[190:193], 0
	v_mfma_f32_16x16x32_bf16 v[20:23], v[166:169], v[208:211], 0
	v_mfma_f32_16x16x32_bf16 v[12:15], v[174:177], v[208:211], 0
	v_mfma_f32_16x16x32_bf16 v[4:7], v[166:169], v[216:219], 0
	v_mfma_f32_16x16x32_bf16 v[0:3], v[174:177], v[216:219], 0
	v_mfma_f32_16x16x32_bf16 v[54:57], v[170:173], v[186:189], v[54:57]
	v_mfma_f32_16x16x32_bf16 v[46:49], v[178:181], v[186:189], v[46:49]
	v_mfma_f32_16x16x32_bf16 v[38:41], v[170:173], v[204:207], v[38:41]
	v_mfma_f32_16x16x32_bf16 v[28:31], v[178:181], v[204:207], v[28:31]
	v_mfma_f32_16x16x32_bf16 v[20:23], v[170:173], v[212:215], v[20:23]
	v_mfma_f32_16x16x32_bf16 v[12:15], v[178:181], v[212:215], v[12:15]
	v_mfma_f32_16x16x32_bf16 v[4:7], v[170:173], v[220:223], v[4:7]
	v_mfma_f32_16x16x32_bf16 v[0:3], v[178:181], v[220:223], v[0:3]
	s_setprio 0
	s_barrier
	s_add_i32 s66, 0, 0x18000
	v_add_u32_e32 v144, s66, v145
	s_add_i32 s67, 0, 0x1c000
	ds_read_b128 v[150:153], v144
	ds_read_b128 v[154:157], v144 offset:1024
	ds_read_b128 v[158:161], v144 offset:2048
	ds_read_b128 v[162:165], v144 offset:3072
	v_add_u32_e32 v144, s67, v145
	ds_read_b128 v[166:169], v144
	ds_read_b128 v[170:173], v144 offset:1024
	ds_read_b128 v[174:177], v144 offset:2048
	ds_read_b128 v[178:181], v144 offset:3072
	s_add_u32 s50, s50, 0x40000
	s_addc_u32 s51, s51, 0
	s_mov_b32 m0, s55
	v_lshl_add_u64 v[238:239], s[50:51], 0, v[136:137]
	ds_read_b128 v[182:185], v149 offset:32768
	ds_read_b128 v[186:189], v149 offset:33792
	ds_read_b128 v[190:193], v149 offset:34816
	ds_read_b128 v[204:207], v149 offset:35840
	ds_read_b128 v[208:211], v149 offset:36864
	ds_read_b128 v[212:215], v149 offset:37888
	ds_read_b128 v[216:219], v149 offset:38912
	ds_read_b128 v[220:223], v149 offset:39936
	global_load_lds_dwordx4 v[238:239], off
	v_lshl_add_u64 v[238:239], s[50:51], 0, v[132:133]
	s_mov_b32 m0, s56
	s_nop 0
	global_load_lds_dwordx4 v[238:239], off
	s_waitcnt vmcnt(8)
	s_waitcnt lgkmcnt(0)
	s_barrier
	s_setprio 1
	s_waitcnt lgkmcnt(0)
	v_mfma_f32_16x16x32_bf16 v[126:129], v[150:153], v[182:185], v[126:129]
	v_mfma_f32_16x16x32_bf16 v[122:125], v[158:161], v[182:185], v[122:125]
	v_mfma_f32_16x16x32_bf16 v[114:117], v[150:153], v[190:193], v[114:117]
	v_mfma_f32_16x16x32_bf16 v[106:109], v[158:161], v[190:193], v[106:109]
	v_mfma_f32_16x16x32_bf16 v[98:101], v[150:153], v[208:211], v[98:101]
	v_mfma_f32_16x16x32_bf16 v[90:93], v[158:161], v[208:211], v[90:93]
	v_mfma_f32_16x16x32_bf16 v[82:85], v[150:153], v[216:219], v[82:85]
	v_mfma_f32_16x16x32_bf16 v[74:77], v[158:161], v[216:219], v[74:77]
	v_mfma_f32_16x16x32_bf16 v[126:129], v[154:157], v[186:189], v[126:129]
	v_mfma_f32_16x16x32_bf16 v[122:125], v[162:165], v[186:189], v[122:125]
	v_mfma_f32_16x16x32_bf16 v[114:117], v[154:157], v[204:207], v[114:117]
	v_mfma_f32_16x16x32_bf16 v[106:109], v[162:165], v[204:207], v[106:109]
	v_mfma_f32_16x16x32_bf16 v[98:101], v[154:157], v[212:215], v[98:101]
	v_mfma_f32_16x16x32_bf16 v[90:93], v[162:165], v[212:215], v[90:93]
	v_mfma_f32_16x16x32_bf16 v[82:85], v[154:157], v[220:223], v[82:85]
	v_mfma_f32_16x16x32_bf16 v[74:77], v[162:165], v[220:223], v[74:77]
	s_setprio 0
	s_setprio 1
	v_mfma_f32_16x16x32_bf16 v[118:121], v[166:169], v[182:185], v[118:121]
	v_mfma_f32_16x16x32_bf16 v[110:113], v[174:177], v[182:185], v[110:113]
	v_mfma_f32_16x16x32_bf16 v[102:105], v[166:169], v[190:193], v[102:105]
	v_mfma_f32_16x16x32_bf16 v[94:97], v[174:177], v[190:193], v[94:97]
	v_mfma_f32_16x16x32_bf16 v[86:89], v[166:169], v[208:211], v[86:89]
	v_mfma_f32_16x16x32_bf16 v[78:81], v[174:177], v[208:211], v[78:81]
	v_mfma_f32_16x16x32_bf16 v[70:73], v[166:169], v[216:219], v[70:73]
	v_mfma_f32_16x16x32_bf16 v[66:69], v[174:177], v[216:219], v[66:69]
	v_mfma_f32_16x16x32_bf16 v[118:121], v[170:173], v[186:189], v[118:121]
	v_mfma_f32_16x16x32_bf16 v[110:113], v[178:181], v[186:189], v[110:113]
	v_mfma_f32_16x16x32_bf16 v[102:105], v[170:173], v[204:207], v[102:105]
	v_mfma_f32_16x16x32_bf16 v[94:97], v[178:181], v[204:207], v[94:97]
	v_mfma_f32_16x16x32_bf16 v[86:89], v[170:173], v[212:215], v[86:89]
	v_mfma_f32_16x16x32_bf16 v[78:81], v[178:181], v[212:215], v[78:81]
	v_mfma_f32_16x16x32_bf16 v[70:73], v[170:173], v[220:223], v[70:73]
	v_mfma_f32_16x16x32_bf16 v[66:69], v[178:181], v[220:223], v[66:69]
	s_setprio 0
	s_barrier
; #define PG8_STAGE(bufoff, gbase, voff) do { _Pragma("unroll") for (int _i = 0; _i < 2; ++_i) \
;         __builtin_amdgcn_global_load_lds((const unsigned*)((const char*)(gbase) + (voff)[_i]), (PG8_LAS unsigned*)(lds + (bufoff) + ldsw + _i * 8192), 16, 0, 0); } while (0)
; #define PG8_LDA(dst, b, h) do { _Pragma("unroll") for (int m = 0; m < 4; ++m) _Pragma("unroll") for (int k = 0; k < 2; ++k) dst[m][k] = *(const PG8_LAS bf16x8*)(lds + PG8_SA(b, h) + aoff + m * 2048 + k * 1024); } while (0)
; #define PG8_MMA(ai, bj, At, Bt) do { __builtin_amdgcn_s_setprio(1); _Pragma("unroll") for (int m = 0; m < 4; ++m) _Pragma("unroll") for (int n = 0; n < 2; ++n) _Pragma("unroll") for (int k = 0; k < 2; ++k) \
;         acc[ai][bj][m][n] = __builtin_amdgcn_mfma_f32_16x16x32_bf16(Bt[n][k], At[m][k], acc[ai][bj][m][n], 0, 0, 0); __builtin_amdgcn_s_setprio(0); } while (0)
; #define PG8_WAIT_V(n) asm volatile("s_waitcnt vmcnt(" #n ")" ::: "memory")
; #define PG8_WAIT_L(n) asm volatile("s_waitcnt lgkmcnt(" #n ")" ::: "memory")
; #define PG8_BAR __builtin_amdgcn_s_barrier()
; #define PG8_SCHED __builtin_amdgcn_sched_barrier(0)
; template <class Epi, class Sched, bool ALIGN_EPI = false, bool SP2 = false>
; __device__ __forceinline__ void gemm_phase(PG8_LAS unsigned char* lds, const Gemm g, const Sched& S, const Epi& E) {
;     ...
;         for (int t = 0; t < nt; t += 2) {
;     ...
;             PG8_WAIT_V(8); PG8_WAIT_L(0); PG8_BAR; PG8_MMA(0, 0, At, B0); PG8_MMA(0, 1, At, B1); PG8_BAR; PG8_SCHED;
;             PG8_LDA(At, 1, 1); PG8_STAGE(PG8_SB(1, 0), b3, voffB); PG8_STAGE(PG8_SB(1, 1), b3 + hstep, voffB); PG8_STAGE(PG8_SA(1, 0), a3, voffA);
;             PG8_WAIT_V(8); PG8_WAIT_L(0); PG8_BAR; PG8_MMA(1, 0, At, B0); PG8_MMA(1, 1, At, B1); PG8_BAR; PG8_SCHED;
	s_add_i32 s50, s66, s45
	v_lshl_add_u64 v[142:143], v[142:143], 0, s[8:9]
	s_mov_b32 m0, s50
	ds_read_b128 v[182:185], v149 offset:49152
	ds_read_b128 v[186:189], v149 offset:50176
	ds_read_b128 v[190:193], v149 offset:51200
	ds_read_b128 v[204:207], v149 offset:52224
	ds_read_b128 v[208:211], v149 offset:53248
	ds_read_b128 v[212:215], v149 offset:54272
	ds_read_b128 v[216:219], v149 offset:55296
	ds_read_b128 v[220:223], v149 offset:56320
	global_load_lds_dwordx4 v[142:143], off
	s_add_i32 m0, s50, 0x2000
	s_add_u32 s46, s46, 0x40080
	v_lshl_add_u64 v[142:143], v[146:147], 0, s[8:9]
	s_addc_u32 s47, s47, 0
	s_add_i32 s50, s67, s45
	global_load_lds_dwordx4 v[142:143], off
	v_lshl_add_u64 v[142:143], s[46:47], 0, v[134:135]
	s_mov_b32 m0, s50
	s_nop 0
	global_load_lds_dwordx4 v[142:143], off
	v_lshl_add_u64 v[142:143], s[46:47], 0, v[130:131]
	s_add_i32 m0, s50, 0x2000
	s_nop 0
	global_load_lds_dwordx4 v[142:143], off
	v_lshl_add_u64 v[142:143], v[224:225], 0, s[8:9]
	s_mov_b32 m0, s58
	s_nop 0
	global_load_lds_dwordx4 v[142:143], off
	v_lshl_add_u64 v[142:143], v[226:227], 0, s[8:9]
	s_mov_b32 m0, s59
	s_nop 0
	global_load_lds_dwordx4 v[142:143], off
	s_waitcnt vmcnt(8)
	s_waitcnt lgkmcnt(0)
	s_barrier
	s_setprio 1
	s_waitcnt lgkmcnt(0)
	v_mfma_f32_16x16x32_bf16 v[62:65], v[150:153], v[182:185], v[62:65]
	v_mfma_f32_16x16x32_bf16 v[58:61], v[158:161], v[182:185], v[58:61]
	v_mfma_f32_16x16x32_bf16 v[50:53], v[150:153], v[190:193], v[50:53]
	v_mfma_f32_16x16x32_bf16 v[42:45], v[158:161], v[190:193], v[42:45]
	v_mfma_f32_16x16x32_bf16 v[34:37], v[150:153], v[208:211], v[34:37]
	v_mfma_f32_16x16x32_bf16 v[24:27], v[158:161], v[208:211], v[24:27]
	v_mfma_f32_16x16x32_bf16 v[16:19], v[150:153], v[216:219], v[16:19]
	v_mfma_f32_16x16x32_bf16 v[8:11], v[158:161], v[216:219], v[8:11]
	v_mfma_f32_16x16x32_bf16 v[62:65], v[154:157], v[186:189], v[62:65]
	v_mfma_f32_16x16x32_bf16 v[58:61], v[162:165], v[186:189], v[58:61]
	v_mfma_f32_16x16x32_bf16 v[50:53], v[154:157], v[204:207], v[50:53]
	v_mfma_f32_16x16x32_bf16 v[42:45], v[162:165], v[204:207], v[42:45]
	v_mfma_f32_16x16x32_bf16 v[34:37], v[154:157], v[212:215], v[34:37]
	v_mfma_f32_16x16x32_bf16 v[24:27], v[162:165], v[212:215], v[24:27]
	v_mfma_f32_16x16x32_bf16 v[16:19], v[154:157], v[220:223], v[16:19]
	v_mfma_f32_16x16x32_bf16 v[8:11], v[162:165], v[220:223], v[8:11]
	s_setprio 0
	s_setprio 1
	v_mfma_f32_16x16x32_bf16 v[54:57], v[166:169], v[182:185], v[54:57]
	v_mfma_f32_16x16x32_bf16 v[46:49], v[174:177], v[182:185], v[46:49]
	v_mfma_f32_16x16x32_bf16 v[38:41], v[166:169], v[190:193], v[38:41]
	v_mfma_f32_16x16x32_bf16 v[28:31], v[174:177], v[190:193], v[28:31]
	v_mfma_f32_16x16x32_bf16 v[20:23], v[166:169], v[208:211], v[20:23]
	v_mfma_f32_16x16x32_bf16 v[12:15], v[174:177], v[208:211], v[12:15]
	v_mfma_f32_16x16x32_bf16 v[4:7], v[166:169], v[216:219], v[4:7]
	v_mfma_f32_16x16x32_bf16 v[0:3], v[174:177], v[216:219], v[0:3]
	v_mfma_f32_16x16x32_bf16 v[54:57], v[170:173], v[186:189], v[54:57]
	v_mfma_f32_16x16x32_bf16 v[46:49], v[178:181], v[186:189], v[46:49]
	v_mfma_f32_16x16x32_bf16 v[38:41], v[170:173], v[204:207], v[38:41]
	v_mfma_f32_16x16x32_bf16 v[28:31], v[178:181], v[204:207], v[28:31]
	v_mfma_f32_16x16x32_bf16 v[20:23], v[170:173], v[212:215], v[20:23]
	v_mfma_f32_16x16x32_bf16 v[12:15], v[178:181], v[212:215], v[12:15]
	v_mfma_f32_16x16x32_bf16 v[4:7], v[170:173], v[220:223], v[4:7]
	v_mfma_f32_16x16x32_bf16 v[0:3], v[178:181], v[220:223], v[0:3]
	s_setprio 0
	s_barrier
	s_add_i32 s65, s65, 2
	s_add_u32 s90, s90, 0x100
	s_addc_u32 s91, s91, 0
	s_add_u32 s63, s63, 0x100
	s_addc_u32 s64, s64, 0
	s_cmp_gt_u32 s65, 13
	s_cbranch_scc1 .Lgx0
.LBB0_145:
	s_add_u32 s46, s90, 0xfffc0080
	s_addc_u32 s47, s91, -1
	s_add_i32 s66, 0, 0x10000
	s_cmp_eq_u32 s65, 12
	s_cselect_b32 s51, s31, s47
	s_cselect_b32 s50, s43, s46
	v_add_u32_e32 v142, s66, v145
	s_cselect_b32 s47, s29, s64
	s_cselect_b32 s46, s62, s63
	s_add_i32 s68, 0, 0x14000
	ds_read_b128 v[150:153], v142
	ds_read_b128 v[154:157], v142 offset:1024
	ds_read_b128 v[158:161], v142 offset:2048
	ds_read_b128 v[162:165], v142 offset:3072
	v_add_u32_e32 v142, s68, v145
	ds_read_b128 v[166:169], v142
	ds_read_b128 v[170:173], v142 offset:1024
	ds_read_b128 v[174:177], v142 offset:2048
	ds_read_b128 v[178:181], v142 offset:3072
	v_lshl_add_u64 v[142:143], s[90:91], 0, v[138:139]
	s_add_i32 m0, s52, 0xc000
	ds_read_b128 v[182:185], v149
	ds_read_b128 v[186:189], v149 offset:1024
	ds_read_b128 v[190:193], v149 offset:2048
	ds_read_b128 v[204:207], v149 offset:3072
	ds_read_b128 v[208:211], v149 offset:4096
	ds_read_b128 v[212:215], v149 offset:5120
	ds_read_b128 v[216:219], v149 offset:6144
	ds_read_b128 v[220:223], v149 offset:7168
	global_load_lds_dwordx4 v[142:143], off
	v_lshl_add_u64 v[142:143], s[90:91], 0, v[140:141]
	s_add_i32 m0, s52, 0xe000
	s_nop 0
	global_load_lds_dwordx4 v[142:143], off
	s_waitcnt vmcnt(8)
	s_waitcnt lgkmcnt(0)
	s_barrier
; #define PG8_STAGE(bufoff, gbase, voff) do { _Pragma("unroll") for (int _i = 0; _i < 2; ++_i) \
;         __builtin_amdgcn_global_load_lds((const unsigned*)((const char*)(gbase) + (voff)[_i]), (PG8_LAS unsigned*)(lds + (bufoff) + ldsw + _i * 8192), 16, 0, 0); } while (0)
; #define PG8_LDA(dst, b, h) do { _Pragma("unroll") for (int m = 0; m < 4; ++m) _Pragma("unroll") for (int k = 0; k < 2; ++k) dst[m][k] = *(const PG8_LAS bf16x8*)(lds + PG8_SA(b, h) + aoff + m * 2048 + k * 1024); } while (0)
; #define PG8_LDB(dst, b, h) do { _Pragma("unroll") for (int n = 0; n < 2; ++n) _Pragma("unroll") for (int k = 0; k < 2; ++k) dst[n][k] = *(const PG8_LAS bf16x8*)(lds + PG8_SB(b, h) + boff + n * 2048 + k * 1024); } while (0)
; #define PG8_MMA(ai, bj, At, Bt) do { __builtin_amdgcn_s_setprio(1); _Pragma("unroll") for (int m = 0; m < 4; ++m) _Pragma("unroll") for (int n = 0; n < 2; ++n) _Pragma("unroll") for (int k = 0; k < 2; ++k) \
;         acc[ai][bj][m][n] = __builtin_amdgcn_mfma_f32_16x16x32_bf16(Bt[n][k], At[m][k], acc[ai][bj][m][n], 0, 0, 0); __builtin_amdgcn_s_setprio(0); } while (0)
; #define PG8_WAIT_V(n) asm volatile("s_waitcnt vmcnt(" #n ")" ::: "memory")
; #define PG8_WAIT_L(n) asm volatile("s_waitcnt lgkmcnt(" #n ")" ::: "memory")
; #define PG8_BAR __builtin_amdgcn_s_barrier()
; #define PG8_SCHED __builtin_amdgcn_sched_barrier(0)
; template <class Epi, class Sched, bool ALIGN_EPI = false, bool SP2 = false>
; __device__ __forceinline__ void gemm_phase(PG8_LAS unsigned char* lds, const Gemm g, const Sched& S, const Epi& E) {
;     ...
;             if constexpr (SP2) {
;             PG8_LDB(B0, 0, 0); PG8_LDB(B1, 0, 1); PG8_SCHED; PG8_LDA(At, 0, 0); PG8_STAGE(PG8_SA(1, 1), a1 + hstep, voffA);
;             PG8_WAIT_V(8); PG8_WAIT_L(0); PG8_BAR; PG8_MMA(0, 0, At, B0); PG8_MMA(0, 1, At, B1); PG8_BAR; PG8_SCHED;
;             PG8_LDA(At, 0, 1); PG8_STAGE(PG8_SB(0, 0), b2, voffB); PG8_STAGE(PG8_SB(0, 1), b2 + hstep, voffB); PG8_STAGE(PG8_SA(0, 0), a2, voffA);
;             PG8_WAIT_V(8); PG8_WAIT_L(0); PG8_BAR; PG8_MMA(1, 0, At, B0); PG8_MMA(1, 1, At, B1); PG8_BAR; PG8_SCHED;
;             PG8_LDB(B0, 1, 0); PG8_LDB(B1, 1, 1); PG8_SCHED; PG8_LDA(At, 1, 0); PG8_STAGE(PG8_SA(0, 1), a2 + hstep, voffA);
;             PG8_WAIT_V(8); PG8_WAIT_L(0); PG8_BAR; PG8_MMA(0, 0, At, B0); PG8_MMA(0, 1, At, B1); PG8_BAR; PG8_SCHED;
	s_setprio 1
	s_waitcnt lgkmcnt(0)
	v_mfma_f32_16x16x32_bf16 v[126:129], v[150:153], v[182:185], v[126:129]
	v_mfma_f32_16x16x32_bf16 v[122:125], v[158:161], v[182:185], v[122:125]
	v_mfma_f32_16x16x32_bf16 v[114:117], v[150:153], v[190:193], v[114:117]
	v_mfma_f32_16x16x32_bf16 v[106:109], v[158:161], v[190:193], v[106:109]
	v_mfma_f32_16x16x32_bf16 v[98:101], v[150:153], v[208:211], v[98:101]
	v_mfma_f32_16x16x32_bf16 v[90:93], v[158:161], v[208:211], v[90:93]
	v_mfma_f32_16x16x32_bf16 v[82:85], v[150:153], v[216:219], v[82:85]
	v_mfma_f32_16x16x32_bf16 v[74:77], v[158:161], v[216:219], v[74:77]
	v_mfma_f32_16x16x32_bf16 v[126:129], v[154:157], v[186:189], v[126:129]
	v_mfma_f32_16x16x32_bf16 v[122:125], v[162:165], v[186:189], v[122:125]
	v_mfma_f32_16x16x32_bf16 v[114:117], v[154:157], v[204:207], v[114:117]
	v_mfma_f32_16x16x32_bf16 v[106:109], v[162:165], v[204:207], v[106:109]
	v_mfma_f32_16x16x32_bf16 v[98:101], v[154:157], v[212:215], v[98:101]
	v_mfma_f32_16x16x32_bf16 v[90:93], v[162:165], v[212:215], v[90:93]
	v_mfma_f32_16x16x32_bf16 v[82:85], v[154:157], v[220:223], v[82:85]
	v_mfma_f32_16x16x32_bf16 v[74:77], v[162:165], v[220:223], v[74:77]
	s_setprio 0
	s_setprio 1
	v_mfma_f32_16x16x32_bf16 v[118:121], v[166:169], v[182:185], v[118:121]
	v_mfma_f32_16x16x32_bf16 v[110:113], v[174:177], v[182:185], v[110:113]
	v_mfma_f32_16x16x32_bf16 v[102:105], v[166:169], v[190:193], v[102:105]
	v_mfma_f32_16x16x32_bf16 v[94:97], v[174:177], v[190:193], v[94:97]
	v_mfma_f32_16x16x32_bf16 v[86:89], v[166:169], v[208:211], v[86:89]
	v_mfma_f32_16x16x32_bf16 v[78:81], v[174:177], v[208:211], v[78:81]
	v_mfma_f32_16x16x32_bf16 v[70:73], v[166:169], v[216:219], v[70:73]
	v_mfma_f32_16x16x32_bf16 v[66:69], v[174:177], v[216:219], v[66:69]
	v_mfma_f32_16x16x32_bf16 v[118:121], v[170:173], v[186:189], v[118:121]
	v_mfma_f32_16x16x32_bf16 v[110:113], v[178:181], v[186:189], v[110:113]
	v_mfma_f32_16x16x32_bf16 v[102:105], v[170:173], v[204:207], v[102:105]
	v_mfma_f32_16x16x32_bf16 v[94:97], v[178:181], v[204:207], v[94:97]
	v_mfma_f32_16x16x32_bf16 v[86:89], v[170:173], v[212:215], v[86:89]
	v_mfma_f32_16x16x32_bf16 v[78:81], v[178:181], v[212:215], v[78:81]
	v_mfma_f32_16x16x32_bf16 v[70:73], v[170:173], v[220:223], v[70:73]
	v_mfma_f32_16x16x32_bf16 v[66:69], v[178:181], v[220:223], v[66:69]
	s_setprio 0
	s_barrier
	s_add_i32 s66, s66, s45
	v_lshl_add_u64 v[142:143], s[46:47], 0, v[134:135]
	s_mov_b32 m0, s66
	ds_read_b128 v[182:185], v149 offset:16384
	ds_read_b128 v[186:189], v149 offset:17408
	ds_read_b128 v[190:193], v149 offset:18432
	ds_read_b128 v[204:207], v149 offset:19456
	ds_read_b128 v[208:211], v149 offset:20480
	ds_read_b128 v[212:215], v149 offset:21504
	ds_read_b128 v[216:219], v149 offset:22528
	ds_read_b128 v[220:223], v149 offset:23552
	global_load_lds_dwordx4 v[142:143], off
	s_add_i32 m0, s66, 0x2000
	s_add_u32 s66, s46, 0x40000
	v_lshl_add_u64 v[146:147], s[46:47], 0, v[130:131]
	s_addc_u32 s67, s47, 0
	s_add_i32 s68, s68, s45
	global_load_lds_dwordx4 v[146:147], off
	v_lshl_add_u64 v[224:225], s[66:67], 0, v[134:135]
	s_mov_b32 m0, s68
	v_lshl_add_u64 v[226:227], s[50:51], 0, v[132:133]
	global_load_lds_dwordx4 v[224:225], off
	v_lshl_add_u64 v[224:225], s[66:67], 0, v[130:131]
	s_add_i32 m0, s68, 0x2000
	s_nop 0
	global_load_lds_dwordx4 v[224:225], off
	v_lshl_add_u64 v[224:225], s[50:51], 0, v[136:137]
	s_mov_b32 m0, s52
	s_nop 0
	global_load_lds_dwordx4 v[224:225], off
	s_mov_b32 m0, s53
	s_nop 0
	global_load_lds_dwordx4 v[226:227], off
	s_waitcnt vmcnt(8)
	s_waitcnt lgkmcnt(0)
	s_barrier
	s_setprio 1
	s_waitcnt lgkmcnt(0)
	v_mfma_f32_16x16x32_bf16 v[62:65], v[150:153], v[182:185], v[62:65]
	v_mfma_f32_16x16x32_bf16 v[58:61], v[158:161], v[182:185], v[58:61]
	v_mfma_f32_16x16x32_bf16 v[50:53], v[150:153], v[190:193], v[50:53]
	v_mfma_f32_16x16x32_bf16 v[42:45], v[158:161], v[190:193], v[42:45]
	v_mfma_f32_16x16x32_bf16 v[34:37], v[150:153], v[208:211], v[34:37]
	v_mfma_f32_16x16x32_bf16 v[24:27], v[158:161], v[208:211], v[24:27]
	v_mfma_f32_16x16x32_bf16 v[16:19], v[150:153], v[216:219], v[16:19]
	v_mfma_f32_16x16x32_bf16 v[8:11], v[158:161], v[216:219], v[8:11]
	v_mfma_f32_16x16x32_bf16 v[62:65], v[154:157], v[186:189], v[62:65]
	v_mfma_f32_16x16x32_bf16 v[58:61], v[162:165], v[186:189], v[58:61]
	v_mfma_f32_16x16x32_bf16 v[50:53], v[154:157], v[204:207], v[50:53]
	v_mfma_f32_16x16x32_bf16 v[42:45], v[162:165], v[204:207], v[42:45]
	v_mfma_f32_16x16x32_bf16 v[34:37], v[154:157], v[212:215], v[34:37]
	v_mfma_f32_16x16x32_bf16 v[24:27], v[162:165], v[212:215], v[24:27]
	v_mfma_f32_16x16x32_bf16 v[16:19], v[154:157], v[220:223], v[16:19]
	v_mfma_f32_16x16x32_bf16 v[8:11], v[162:165], v[220:223], v[8:11]
	s_setprio 0
	s_setprio 1
	v_mfma_f32_16x16x32_bf16 v[54:57], v[166:169], v[182:185], v[54:57]
	v_mfma_f32_16x16x32_bf16 v[46:49], v[174:177], v[182:185], v[46:49]
	v_mfma_f32_16x16x32_bf16 v[38:41], v[166:169], v[190:193], v[38:41]
	v_mfma_f32_16x16x32_bf16 v[28:31], v[174:177], v[190:193], v[28:31]
	v_mfma_f32_16x16x32_bf16 v[20:23], v[166:169], v[208:211], v[20:23]
	v_mfma_f32_16x16x32_bf16 v[12:15], v[174:177], v[208:211], v[12:15]
	v_mfma_f32_16x16x32_bf16 v[4:7], v[166:169], v[216:219], v[4:7]
	v_mfma_f32_16x16x32_bf16 v[0:3], v[174:177], v[216:219], v[0:3]
	v_mfma_f32_16x16x32_bf16 v[54:57], v[170:173], v[186:189], v[54:57]
	v_mfma_f32_16x16x32_bf16 v[46:49], v[178:181], v[186:189], v[46:49]
	v_mfma_f32_16x16x32_bf16 v[38:41], v[170:173], v[204:207], v[38:41]
	v_mfma_f32_16x16x32_bf16 v[28:31], v[178:181], v[204:207], v[28:31]
	v_mfma_f32_16x16x32_bf16 v[20:23], v[170:173], v[212:215], v[20:23]
	v_mfma_f32_16x16x32_bf16 v[12:15], v[178:181], v[212:215], v[12:15]
	v_mfma_f32_16x16x32_bf16 v[4:7], v[170:173], v[220:223], v[4:7]
	v_mfma_f32_16x16x32_bf16 v[0:3], v[178:181], v[220:223], v[0:3]
	s_setprio 0
	s_barrier
; #define PG8_STAGE(bufoff, gbase, voff) do { _Pragma("unroll") for (int _i = 0; _i < 2; ++_i) \
;         __builtin_amdgcn_global_load_lds((const unsigned*)((const char*)(gbase) + (voff)[_i]), (PG8_LAS unsigned*)(lds + (bufoff) + ldsw + _i * 8192), 16, 0, 0); } while (0)
; #define PG8_LDA(dst, b, h) do { _Pragma("unroll") for (int m = 0; m < 4; ++m) _Pragma("unroll") for (int k = 0; k < 2; ++k) dst[m][k] = *(const PG8_LAS bf16x8*)(lds + PG8_SA(b, h) + aoff + m * 2048 + k * 1024); } while (0)
; #define PG8_LDB(dst, b, h) do { _Pragma("unroll") for (int n = 0; n < 2; ++n) _Pragma("unroll") for (int k = 0; k < 2; ++k) dst[n][k] = *(const PG8_LAS bf16x8*)(lds + PG8_SB(b, h) + boff + n * 2048 + k * 1024); } while (0)
; #define PG8_MMA(ai, bj, At, Bt) do { __builtin_amdgcn_s_setprio(1); _Pragma("unroll") for (int m = 0; m < 4; ++m) _Pragma("unroll") for (int n = 0; n < 2; ++n) _Pragma("unroll") for (int k = 0; k < 2; ++k) \
;         acc[ai][bj][m][n] = __builtin_amdgcn_mfma_f32_16x16x32_bf16(Bt[n][k], At[m][k], acc[ai][bj][m][n], 0, 0, 0); __builtin_amdgcn_s_setprio(0); } while (0)
; #define PG8_WAIT_V(n) asm volatile("s_waitcnt vmcnt(" #n ")" ::: "memory")
; #define PG8_WAIT_L(n) asm volatile("s_waitcnt lgkmcnt(" #n ")" ::: "memory")
; #define PG8_BAR __builtin_amdgcn_s_barrier()
; #define PG8_SCHED __builtin_amdgcn_sched_barrier(0)
; template <class Epi, class Sched, bool ALIGN_EPI = false, bool SP2 = false>
; __device__ __forceinline__ void gemm_phase(PG8_LAS unsigned char* lds, const Gemm g, const Sched& S, const Epi& E) {
;     ...
;             PG8_WAIT_V(8); PG8_WAIT_L(0); PG8_BAR; PG8_MMA(1, 0, At, B0); PG8_MMA(1, 1, At, B1); PG8_BAR; PG8_SCHED;
;             PG8_LDB(B0, 1, 0); PG8_LDB(B1, 1, 1); PG8_SCHED; PG8_LDA(At, 1, 0); PG8_STAGE(PG8_SA(0, 1), a2 + hstep, voffA);
;             PG8_WAIT_V(8); PG8_WAIT_L(0); PG8_BAR; PG8_MMA(0, 0, At, B0); PG8_MMA(0, 1, At, B1); PG8_BAR; PG8_SCHED;
	s_add_i32 s66, 0, 0x18000
	v_add_u32_e32 v144, s66, v145
	s_add_i32 s67, 0, 0x1c000
	ds_read_b128 v[150:153], v144
	ds_read_b128 v[154:157], v144 offset:1024
	ds_read_b128 v[158:161], v144 offset:2048
	ds_read_b128 v[162:165], v144 offset:3072
	v_add_u32_e32 v144, s67, v145
	ds_read_b128 v[166:169], v144
	ds_read_b128 v[170:173], v144 offset:1024
	ds_read_b128 v[174:177], v144 offset:2048
	ds_read_b128 v[178:181], v144 offset:3072
	s_add_u32 s50, s50, 0x40000
	s_addc_u32 s51, s51, 0
	s_mov_b32 m0, s55
	v_lshl_add_u64 v[238:239], s[50:51], 0, v[136:137]
	ds_read_b128 v[182:185], v149 offset:32768
	ds_read_b128 v[186:189], v149 offset:33792
	ds_read_b128 v[190:193], v149 offset:34816
	ds_read_b128 v[204:207], v149 offset:35840
	ds_read_b128 v[208:211], v149 offset:36864
	ds_read_b128 v[212:215], v149 offset:37888
	ds_read_b128 v[216:219], v149 offset:38912
	ds_read_b128 v[220:223], v149 offset:39936
	global_load_lds_dwordx4 v[238:239], off
	v_lshl_add_u64 v[238:239], s[50:51], 0, v[132:133]
	s_mov_b32 m0, s56
	s_nop 0
	global_load_lds_dwordx4 v[238:239], off
	s_waitcnt vmcnt(8)
	s_waitcnt lgkmcnt(0)
	s_barrier
	s_setprio 1
	s_waitcnt lgkmcnt(0)
	v_mfma_f32_16x16x32_bf16 v[126:129], v[150:153], v[182:185], v[126:129]
	v_mfma_f32_16x16x32_bf16 v[122:125], v[158:161], v[182:185], v[122:125]
	v_mfma_f32_16x16x32_bf16 v[114:117], v[150:153], v[190:193], v[114:117]
	v_mfma_f32_16x16x32_bf16 v[106:109], v[158:161], v[190:193], v[106:109]
	v_mfma_f32_16x16x32_bf16 v[98:101], v[150:153], v[208:211], v[98:101]
	v_mfma_f32_16x16x32_bf16 v[90:93], v[158:161], v[208:211], v[90:93]
	v_mfma_f32_16x16x32_bf16 v[82:85], v[150:153], v[216:219], v[82:85]
	v_mfma_f32_16x16x32_bf16 v[74:77], v[158:161], v[216:219], v[74:77]
	v_mfma_f32_16x16x32_bf16 v[126:129], v[154:157], v[186:189], v[126:129]
	v_mfma_f32_16x16x32_bf16 v[122:125], v[162:165], v[186:189], v[122:125]
	v_mfma_f32_16x16x32_bf16 v[114:117], v[154:157], v[204:207], v[114:117]
	v_mfma_f32_16x16x32_bf16 v[106:109], v[162:165], v[204:207], v[106:109]
	v_mfma_f32_16x16x32_bf16 v[98:101], v[154:157], v[212:215], v[98:101]
	v_mfma_f32_16x16x32_bf16 v[90:93], v[162:165], v[212:215], v[90:93]
	v_mfma_f32_16x16x32_bf16 v[82:85], v[154:157], v[220:223], v[82:85]
	v_mfma_f32_16x16x32_bf16 v[74:77], v[162:165], v[220:223], v[74:77]
	s_setprio 0
	s_setprio 1
	v_mfma_f32_16x16x32_bf16 v[118:121], v[166:169], v[182:185], v[118:121]
	v_mfma_f32_16x16x32_bf16 v[110:113], v[174:177], v[182:185], v[110:113]
	v_mfma_f32_16x16x32_bf16 v[102:105], v[166:169], v[190:193], v[102:105]
	v_mfma_f32_16x16x32_bf16 v[94:97], v[174:177], v[190:193], v[94:97]
	v_mfma_f32_16x16x32_bf16 v[86:89], v[166:169], v[208:211], v[86:89]
	v_mfma_f32_16x16x32_bf16 v[78:81], v[174:177], v[208:211], v[78:81]
	v_mfma_f32_16x16x32_bf16 v[70:73], v[166:169], v[216:219], v[70:73]
	v_mfma_f32_16x16x32_bf16 v[66:69], v[174:177], v[216:219], v[66:69]
	v_mfma_f32_16x16x32_bf16 v[118:121], v[170:173], v[186:189], v[118:121]
	v_mfma_f32_16x16x32_bf16 v[110:113], v[178:181], v[186:189], v[110:113]
	v_mfma_f32_16x16x32_bf16 v[102:105], v[170:173], v[204:207], v[102:105]
	v_mfma_f32_16x16x32_bf16 v[94:97], v[178:181], v[204:207], v[94:97]
	v_mfma_f32_16x16x32_bf16 v[86:89], v[170:173], v[212:215], v[86:89]
	v_mfma_f32_16x16x32_bf16 v[78:81], v[178:181], v[212:215], v[78:81]
	v_mfma_f32_16x16x32_bf16 v[70:73], v[170:173], v[220:223], v[70:73]
	v_mfma_f32_16x16x32_bf16 v[66:69], v[178:181], v[220:223], v[66:69]
	s_setprio 0
	s_barrier
; #define PG8_STAGE(bufoff, gbase, voff) do { _Pragma("unroll") for (int _i = 0; _i < 2; ++_i) \
;         __builtin_amdgcn_global_load_lds((const unsigned*)((const char*)(gbase) + (voff)[_i]), (PG8_LAS unsigned*)(lds + (bufoff) + ldsw + _i * 8192), 16, 0, 0); } while (0)
; #define PG8_LDA(dst, b, h) do { _Pragma("unroll") for (int m = 0; m < 4; ++m) _Pragma("unroll") for (int k = 0; k < 2; ++k) dst[m][k] = *(const PG8_LAS bf16x8*)(lds + PG8_SA(b, h) + aoff + m * 2048 + k * 1024); } while (0)
; #define PG8_MMA(ai, bj, At, Bt) do { __builtin_amdgcn_s_setprio(1); _Pragma("unroll") for (int m = 0; m < 4; ++m) _Pragma("unroll") for (int n = 0; n < 2; ++n) _Pragma("unroll") for (int k = 0; k < 2; ++k) \
;         acc[ai][bj][m][n] = __builtin_amdgcn_mfma_f32_16x16x32_bf16(Bt[n][k], At[m][k], acc[ai][bj][m][n], 0, 0, 0); __builtin_amdgcn_s_setprio(0); } while (0)
; #define PG8_WAIT_V(n) asm volatile("s_waitcnt vmcnt(" #n ")" ::: "memory")
; #define PG8_WAIT_L(n) asm volatile("s_waitcnt lgkmcnt(" #n ")" ::: "memory")
; #define PG8_BAR __builtin_amdgcn_s_barrier()
; #define PG8_SCHED __builtin_amdgcn_sched_barrier(0)
; template <class Epi, class Sched, bool ALIGN_EPI = false, bool SP2 = false>
; __device__ __forceinline__ void gemm_phase(PG8_LAS unsigned char* lds, const Gemm g, const Sched& S, const Epi& E) {
;     ...
;         for (int t = 0; t < nt; t += 2) {
;     ...
;             PG8_WAIT_V(8); PG8_WAIT_L(0); PG8_BAR; PG8_MMA(0, 0, At, B0); PG8_MMA(0, 1, At, B1); PG8_BAR; PG8_SCHED;
;             PG8_LDA(At, 1, 1); PG8_STAGE(PG8_SB(1, 0), b3, voffB); PG8_STAGE(PG8_SB(1, 1), b3 + hstep, voffB); PG8_STAGE(PG8_SA(1, 0), a3, voffA);
;             PG8_WAIT_V(8); PG8_WAIT_L(0); PG8_BAR; PG8_MMA(1, 0, At, B0); PG8_MMA(1, 1, At, B1); PG8_BAR; PG8_SCHED;
;     ...
;         if constexpr (ALIGN_EPI) { if (wr == 0) PG8_BAR; }
	s_add_i32 s50, s66, s45
	v_lshl_add_u64 v[142:143], v[142:143], 0, s[8:9]
	s_mov_b32 m0, s50
	ds_read_b128 v[182:185], v149 offset:49152
	ds_read_b128 v[186:189], v149 offset:50176
	ds_read_b128 v[190:193], v149 offset:51200
	ds_read_b128 v[204:207], v149 offset:52224
	ds_read_b128 v[208:211], v149 offset:53248
	ds_read_b128 v[212:215], v149 offset:54272
	ds_read_b128 v[216:219], v149 offset:55296
	ds_read_b128 v[220:223], v149 offset:56320
	global_load_lds_dwordx4 v[142:143], off
	s_add_i32 m0, s50, 0x2000
	s_add_u32 s46, s46, 0x40080
	v_lshl_add_u64 v[142:143], v[146:147], 0, s[8:9]
	s_addc_u32 s47, s47, 0
	s_add_i32 s50, s67, s45
	global_load_lds_dwordx4 v[142:143], off
	v_lshl_add_u64 v[142:143], s[46:47], 0, v[134:135]
	s_mov_b32 m0, s50
	s_nop 0
	global_load_lds_dwordx4 v[142:143], off
	v_lshl_add_u64 v[142:143], s[46:47], 0, v[130:131]
	s_add_i32 m0, s50, 0x2000
	s_nop 0
	global_load_lds_dwordx4 v[142:143], off
	v_lshl_add_u64 v[142:143], v[224:225], 0, s[8:9]
	s_mov_b32 m0, s58
	s_nop 0
	global_load_lds_dwordx4 v[142:143], off
	v_lshl_add_u64 v[142:143], v[226:227], 0, s[8:9]
	s_mov_b32 m0, s59
	s_nop 0
	global_load_lds_dwordx4 v[142:143], off
	s_waitcnt vmcnt(8)
	s_waitcnt lgkmcnt(0)
	s_barrier
	s_setprio 1
	s_waitcnt lgkmcnt(0)
	v_mfma_f32_16x16x32_bf16 v[62:65], v[150:153], v[182:185], v[62:65]
	v_mfma_f32_16x16x32_bf16 v[58:61], v[158:161], v[182:185], v[58:61]
	v_mfma_f32_16x16x32_bf16 v[50:53], v[150:153], v[190:193], v[50:53]
	v_mfma_f32_16x16x32_bf16 v[42:45], v[158:161], v[190:193], v[42:45]
	v_mfma_f32_16x16x32_bf16 v[34:37], v[150:153], v[208:211], v[34:37]
	v_mfma_f32_16x16x32_bf16 v[24:27], v[158:161], v[208:211], v[24:27]
	v_mfma_f32_16x16x32_bf16 v[16:19], v[150:153], v[216:219], v[16:19]
	v_mfma_f32_16x16x32_bf16 v[8:11], v[158:161], v[216:219], v[8:11]
	v_mfma_f32_16x16x32_bf16 v[62:65], v[154:157], v[186:189], v[62:65]
	v_mfma_f32_16x16x32_bf16 v[58:61], v[162:165], v[186:189], v[58:61]
	v_mfma_f32_16x16x32_bf16 v[50:53], v[154:157], v[204:207], v[50:53]
	v_mfma_f32_16x16x32_bf16 v[42:45], v[162:165], v[204:207], v[42:45]
	v_mfma_f32_16x16x32_bf16 v[34:37], v[154:157], v[212:215], v[34:37]
	v_mfma_f32_16x16x32_bf16 v[24:27], v[162:165], v[212:215], v[24:27]
	v_mfma_f32_16x16x32_bf16 v[16:19], v[154:157], v[220:223], v[16:19]
	v_mfma_f32_16x16x32_bf16 v[8:11], v[162:165], v[220:223], v[8:11]
	s_setprio 0
	s_setprio 1
	v_mfma_f32_16x16x32_bf16 v[54:57], v[166:169], v[182:185], v[54:57]
	v_mfma_f32_16x16x32_bf16 v[46:49], v[174:177], v[182:185], v[46:49]
	v_mfma_f32_16x16x32_bf16 v[38:41], v[166:169], v[190:193], v[38:41]
	v_mfma_f32_16x16x32_bf16 v[28:31], v[174:177], v[190:193], v[28:31]
	v_mfma_f32_16x16x32_bf16 v[20:23], v[166:169], v[208:211], v[20:23]
	v_mfma_f32_16x16x32_bf16 v[12:15], v[174:177], v[208:211], v[12:15]
	v_mfma_f32_16x16x32_bf16 v[4:7], v[166:169], v[216:219], v[4:7]
	v_mfma_f32_16x16x32_bf16 v[0:3], v[174:177], v[216:219], v[0:3]
	v_mfma_f32_16x16x32_bf16 v[54:57], v[170:173], v[186:189], v[54:57]
	v_mfma_f32_16x16x32_bf16 v[46:49], v[178:181], v[186:189], v[46:49]
	v_mfma_f32_16x16x32_bf16 v[38:41], v[170:173], v[204:207], v[38:41]
	v_mfma_f32_16x16x32_bf16 v[28:31], v[178:181], v[204:207], v[28:31]
	v_mfma_f32_16x16x32_bf16 v[20:23], v[170:173], v[212:215], v[20:23]
	v_mfma_f32_16x16x32_bf16 v[12:15], v[178:181], v[212:215], v[12:15]
	v_mfma_f32_16x16x32_bf16 v[4:7], v[170:173], v[220:223], v[4:7]
	v_mfma_f32_16x16x32_bf16 v[0:3], v[178:181], v[220:223], v[0:3]
	s_setprio 0
	s_barrier
	s_add_i32 s65, s65, 2
	s_add_u32 s90, s90, 0x100
	s_addc_u32 s91, s91, 0
	s_add_u32 s63, s63, 0x100
	s_addc_u32 s64, s64, 0
	s_cmp_gt_u32 s65, 13
	s_cbranch_scc0 .LBB0_145
.Lgx0:
	s_and_b64 vcc, exec, s[26:27]
	s_cbranch_vccz .LBB0_148
	s_barrier

; #define PG8_STAGE(bufoff, gbase, voff) do { _Pragma("unroll") for (int _i = 0; _i < 2; ++_i) \
;         __builtin_amdgcn_global_load_lds((const unsigned*)((const char*)(gbase) + (voff)[_i]), (PG8_LAS unsigned*)(lds + (bufoff) + ldsw + _i * 8192), 16, 0, 0); } while (0)
; #define PG8_LDA(dst, b, h) do { _Pragma("unroll") for (int m = 0; m < 4; ++m) _Pragma("unroll") for (int k = 0; k < 2; ++k) dst[m][k] = *(const PG8_LAS bf16x8*)(lds + PG8_SA(b, h) + aoff + m * 2048 + k * 1024); } while (0)
; #define PG8_LDB(dst, b, h) do { _Pragma("unroll") for (int n = 0; n < 2; ++n) _Pragma("unroll") for (int k = 0; k < 2; ++k) dst[n][k] = *(const PG8_LAS bf16x8*)(lds + PG8_SB(b, h) + boff + n * 2048 + k * 1024); } while (0)
; #define PG8_WAIT_V(n) asm volatile("s_waitcnt vmcnt(" #n ")" ::: "memory")
; #define PG8_WAIT_L(n) asm volatile("s_waitcnt lgkmcnt(" #n ")" ::: "memory")
; #define PG8_BAR __builtin_amdgcn_s_barrier()
; #define PG8_SCHED __builtin_amdgcn_sched_barrier(0)
; template <class Epi, class Sched, bool ALIGN_EPI = false, bool SP2 = false>
; __device__ __forceinline__ void gemm_phase(PG8_LAS unsigned char* lds, const Gemm g, const Sched& S, const Epi& E) {
;     ...
;         const bool has_next = S.next(ui + 1, nxt);
;         const char* nA = has_next ? (const char*)g.A + (size_t)nxt.pm * tstep : cA; const char* nB = has_next ? (const char*)g.Bt + (size_t)nxt.pn * tstep : cB;
;         for (int t = 0; t < nt; t += 2) {
;             const bool last = (t == nt - 2);
;             const char* a1 = cA + (size_t)(t + 1) * kstep;
;             const char* a2 = last ? nA : cA + (size_t)(t + 2) * kstep; const char* b2 = last ? nB : cB + (size_t)(t + 2) * kstep;
;             const char* a3 = a2 + kstep; const char* b3 = b2 + kstep;
;             if (last && has_next) S.a_ready(nxt);
;             if constexpr (SP2) {
;             PG8_LDB(B0, 0, 0); PG8_LDB(B1, 0, 1); PG8_SCHED; PG8_LDA(At, 0, 0); PG8_STAGE(PG8_SA(1, 1), a1 + hstep, voffA);
;             PG8_WAIT_V(8); PG8_WAIT_L(0); PG8_BAR; PG8_MMA(0, 0, At, B0); PG8_MMA(0, 1, At, B1); PG8_BAR; PG8_SCHED;
;             PG8_LDA(At, 0, 1); PG8_STAGE(PG8_SB(0, 0), b2, voffB); PG8_STAGE(PG8_SB(0, 1), b2 + hstep, voffB); PG8_STAGE(PG8_SA(0, 0), a2, voffA);
;             PG8_WAIT_V(8); PG8_WAIT_L(0); PG8_BAR; PG8_MMA(1, 0, At, B0); PG8_MMA(1, 1, At, B1); PG8_BAR; PG8_SCHED;
.LBB0_548:
	s_ashr_i32 s91, s90, 31
	s_lshl_b64 s[6:7], s[90:91], 19
	s_add_u32 s46, s19, s6
	s_addc_u32 s47, s44, s7
	s_and_b64 s[6:7], s[40:41], exec
	s_cselect_b32 s35, s47, s37
	s_cselect_b32 s62, s46, s36
	s_ashr_i32 s43, s42, 31
	s_lshl_b64 s[6:7], s[42:43], 19
	s_add_u32 s6, s45, s6
	s_addc_u32 s7, s55, s7
	s_and_b64 s[64:65], s[40:41], exec
	s_cselect_b32 s43, s7, s51
	s_cselect_b32 s63, s6, s50
	s_add_u32 vcc_lo, s36, 0x40080
	s_addc_u32 vcc_hi, s37, 0
	s_add_u32 s64, s50, 0x100
	s_addc_u32 s65, s51, 0
	s_mov_b32 s91, -2
	s_add_u32 s36, vcc_lo, 0xfffc0080
	s_addc_u32 s37, vcc_hi, -1
	s_add_i32 s66, 0, 0x10000
	s_cmp_eq_u32 s91, 12
	s_cselect_b32 s51, s35, s37
	s_cselect_b32 s50, s62, s36
	v_add_u32_e32 v148, s66, v150
	s_cselect_b32 s37, s43, s65
	s_cselect_b32 s36, s63, s64
	s_add_i32 s68, 0, 0x14000
	ds_read_b128 v[144:147], v148
	ds_read_b128 v[162:165], v148 offset:1024
	ds_read_b128 v[166:169], v148 offset:2048
	ds_read_b128 v[170:173], v148 offset:3072
	v_add_u32_e32 v148, s68, v150
	ds_read_b128 v[174:177], v148
	ds_read_b128 v[178:181], v148 offset:1024
	ds_read_b128 v[182:185], v148 offset:2048
	ds_read_b128 v[186:189], v148 offset:3072
	v_lshl_add_u64 v[148:149], vcc, 0, v[140:141]
	s_add_i32 m0, s4, 0xc000
	ds_read_b128 v[190:193], v161
	ds_read_b128 v[204:207], v161 offset:1024
	ds_read_b128 v[208:211], v161 offset:2048
	ds_read_b128 v[212:215], v161 offset:3072
	ds_read_b128 v[216:219], v161 offset:4096
	ds_read_b128 v[220:223], v161 offset:5120
	ds_read_b128 v[224:227], v161 offset:6144
	ds_read_b128 v[238:241], v161 offset:7168
	global_load_lds_dwordx4 v[148:149], off
	v_lshl_add_u64 v[148:149], vcc, 0, v[142:143]
	s_add_i32 m0, s4, 0xe000
	s_nop 0
	global_load_lds_dwordx4 v[148:149], off
	s_waitcnt vmcnt(8)
	s_waitcnt lgkmcnt(0)
	s_barrier
	s_setprio 1
	s_waitcnt lgkmcnt(0)
	v_mfma_f32_16x16x32_bf16 v[126:129], v[144:147], v[190:193], 0
	v_mfma_f32_16x16x32_bf16 v[118:121], v[166:169], v[190:193], 0
	v_mfma_f32_16x16x32_bf16 v[110:113], v[144:147], v[208:211], 0
	v_mfma_f32_16x16x32_bf16 v[102:105], v[166:169], v[208:211], 0
	v_mfma_f32_16x16x32_bf16 v[94:97], v[144:147], v[216:219], 0
	v_mfma_f32_16x16x32_bf16 v[86:89], v[166:169], v[216:219], 0
	v_mfma_f32_16x16x32_bf16 v[78:81], v[144:147], v[224:227], 0
	v_mfma_f32_16x16x32_bf16 v[70:73], v[166:169], v[224:227], 0
	v_mfma_f32_16x16x32_bf16 v[126:129], v[162:165], v[204:207], v[126:129]
	v_mfma_f32_16x16x32_bf16 v[118:121], v[170:173], v[204:207], v[118:121]
	v_mfma_f32_16x16x32_bf16 v[110:113], v[162:165], v[212:215], v[110:113]
	v_mfma_f32_16x16x32_bf16 v[102:105], v[170:173], v[212:215], v[102:105]
	v_mfma_f32_16x16x32_bf16 v[94:97], v[162:165], v[220:223], v[94:97]
	v_mfma_f32_16x16x32_bf16 v[86:89], v[170:173], v[220:223], v[86:89]
	v_mfma_f32_16x16x32_bf16 v[78:81], v[162:165], v[238:241], v[78:81]
	v_mfma_f32_16x16x32_bf16 v[70:73], v[170:173], v[238:241], v[70:73]
	s_setprio 0
	s_setprio 1
	v_mfma_f32_16x16x32_bf16 v[122:125], v[174:177], v[190:193], 0
	v_mfma_f32_16x16x32_bf16 v[114:117], v[182:185], v[190:193], 0
	v_mfma_f32_16x16x32_bf16 v[106:109], v[174:177], v[208:211], 0
	v_mfma_f32_16x16x32_bf16 v[98:101], v[182:185], v[208:211], 0
	v_mfma_f32_16x16x32_bf16 v[90:93], v[174:177], v[216:219], 0
	v_mfma_f32_16x16x32_bf16 v[82:85], v[182:185], v[216:219], 0
	v_mfma_f32_16x16x32_bf16 v[74:77], v[174:177], v[224:227], 0
	v_mfma_f32_16x16x32_bf16 v[66:69], v[182:185], v[224:227], 0
	v_mfma_f32_16x16x32_bf16 v[122:125], v[178:181], v[204:207], v[122:125]
	v_mfma_f32_16x16x32_bf16 v[114:117], v[186:189], v[204:207], v[114:117]
	v_mfma_f32_16x16x32_bf16 v[106:109], v[178:181], v[212:215], v[106:109]
	v_mfma_f32_16x16x32_bf16 v[98:101], v[186:189], v[212:215], v[98:101]
	v_mfma_f32_16x16x32_bf16 v[90:93], v[178:181], v[220:223], v[90:93]
	v_mfma_f32_16x16x32_bf16 v[82:85], v[186:189], v[220:223], v[82:85]
	v_mfma_f32_16x16x32_bf16 v[74:77], v[178:181], v[238:241], v[74:77]
	v_mfma_f32_16x16x32_bf16 v[66:69], v[186:189], v[238:241], v[66:69]
	s_setprio 0
	s_barrier
	s_add_i32 s66, s66, s56
	v_lshl_add_u64 v[148:149], s[36:37], 0, v[134:135]
	s_mov_b32 m0, s66
	ds_read_b128 v[190:193], v161 offset:16384
	ds_read_b128 v[204:207], v161 offset:17408
	ds_read_b128 v[208:211], v161 offset:18432
	ds_read_b128 v[212:215], v161 offset:19456
	ds_read_b128 v[216:219], v161 offset:20480
	ds_read_b128 v[220:223], v161 offset:21504
	ds_read_b128 v[224:227], v161 offset:22528
	ds_read_b128 v[238:241], v161 offset:23552
	global_load_lds_dwordx4 v[148:149], off
	s_add_i32 m0, s66, 0x2000
	s_add_u32 s66, s36, 0x40000
	v_lshl_add_u64 v[242:243], s[36:37], 0, v[130:131]
	s_addc_u32 s67, s37, 0
	s_add_i32 s68, s68, s56
	global_load_lds_dwordx4 v[242:243], off
	v_lshl_add_u64 v[244:245], s[66:67], 0, v[134:135]
	s_mov_b32 m0, s68
	v_lshl_add_u64 v[246:247], s[50:51], 0, v[132:133]
	global_load_lds_dwordx4 v[244:245], off
	v_lshl_add_u64 v[244:245], s[66:67], 0, v[130:131]
	s_add_i32 m0, s68, 0x2000
	s_nop 0
	global_load_lds_dwordx4 v[244:245], off
	v_lshl_add_u64 v[244:245], s[50:51], 0, v[136:137]
	s_mov_b32 m0, s4
	s_nop 0
	global_load_lds_dwordx4 v[244:245], off
	s_mov_b32 m0, s5
	s_nop 0
	global_load_lds_dwordx4 v[246:247], off
	s_waitcnt vmcnt(8)
	s_waitcnt lgkmcnt(0)
	s_barrier
; #define PG8_STAGE(bufoff, gbase, voff) do { _Pragma("unroll") for (int _i = 0; _i < 2; ++_i) \
;         __builtin_amdgcn_global_load_lds((const unsigned*)((const char*)(gbase) + (voff)[_i]), (PG8_LAS unsigned*)(lds + (bufoff) + ldsw + _i * 8192), 16, 0, 0); } while (0)
; #define PG8_LDA(dst, b, h) do { _Pragma("unroll") for (int m = 0; m < 4; ++m) _Pragma("unroll") for (int k = 0; k < 2; ++k) dst[m][k] = *(const PG8_LAS bf16x8*)(lds + PG8_SA(b, h) + aoff + m * 2048 + k * 1024); } while (0)
; #define PG8_LDB(dst, b, h) do { _Pragma("unroll") for (int n = 0; n < 2; ++n) _Pragma("unroll") for (int k = 0; k < 2; ++k) dst[n][k] = *(const PG8_LAS bf16x8*)(lds + PG8_SB(b, h) + boff + n * 2048 + k * 1024); } while (0)
; #define PG8_MMA(ai, bj, At, Bt) do { __builtin_amdgcn_s_setprio(1); _Pragma("unroll") for (int m = 0; m < 4; ++m) _Pragma("unroll") for (int n = 0; n < 2; ++n) _Pragma("unroll") for (int k = 0; k < 2; ++k) \
;         acc[ai][bj][m][n] = __builtin_amdgcn_mfma_f32_16x16x32_bf16(Bt[n][k], At[m][k], acc[ai][bj][m][n], 0, 0, 0); __builtin_amdgcn_s_setprio(0); } while (0)
; #define PG8_WAIT_V(n) asm volatile("s_waitcnt vmcnt(" #n ")" ::: "memory")
; #define PG8_WAIT_L(n) asm volatile("s_waitcnt lgkmcnt(" #n ")" ::: "memory")
; #define PG8_BAR __builtin_amdgcn_s_barrier()
; #define PG8_SCHED __builtin_amdgcn_sched_barrier(0)
; template <class Epi, class Sched, bool ALIGN_EPI = false, bool SP2 = false>
; __device__ __forceinline__ void gemm_phase(PG8_LAS unsigned char* lds, const Gemm g, const Sched& S, const Epi& E) {
;     ...
;             PG8_WAIT_V(8); PG8_WAIT_L(0); PG8_BAR; PG8_MMA(0, 0, At, B0); PG8_MMA(0, 1, At, B1); PG8_BAR; PG8_SCHED;
;             PG8_LDA(At, 0, 1); PG8_STAGE(PG8_SB(0, 0), b2, voffB); PG8_STAGE(PG8_SB(0, 1), b2 + hstep, voffB); PG8_STAGE(PG8_SA(0, 0), a2, voffA);
;             PG8_WAIT_V(8); PG8_WAIT_L(0); PG8_BAR; PG8_MMA(1, 0, At, B0); PG8_MMA(1, 1, At, B1); PG8_BAR; PG8_SCHED;
;             PG8_LDB(B0, 1, 0); PG8_LDB(B1, 1, 1); PG8_SCHED; PG8_LDA(At, 1, 0); PG8_STAGE(PG8_SA(0, 1), a2 + hstep, voffA);
;             PG8_WAIT_V(8); PG8_WAIT_L(0); PG8_BAR; PG8_MMA(0, 0, At, B0); PG8_MMA(0, 1, At, B1); PG8_BAR; PG8_SCHED;
	s_setprio 1
	s_waitcnt lgkmcnt(0)
	v_mfma_f32_16x16x32_bf16 v[62:65], v[144:147], v[190:193], 0
	v_mfma_f32_16x16x32_bf16 v[54:57], v[166:169], v[190:193], 0
	v_mfma_f32_16x16x32_bf16 v[46:49], v[144:147], v[208:211], 0
	v_mfma_f32_16x16x32_bf16 v[38:41], v[166:169], v[208:211], 0
	v_mfma_f32_16x16x32_bf16 v[28:31], v[144:147], v[216:219], 0
	v_mfma_f32_16x16x32_bf16 v[20:23], v[166:169], v[216:219], 0
	v_mfma_f32_16x16x32_bf16 v[12:15], v[144:147], v[224:227], 0
	v_mfma_f32_16x16x32_bf16 v[4:7], v[166:169], v[224:227], 0
	v_mfma_f32_16x16x32_bf16 v[62:65], v[162:165], v[204:207], v[62:65]
	v_mfma_f32_16x16x32_bf16 v[54:57], v[170:173], v[204:207], v[54:57]
	v_mfma_f32_16x16x32_bf16 v[46:49], v[162:165], v[212:215], v[46:49]
	v_mfma_f32_16x16x32_bf16 v[38:41], v[170:173], v[212:215], v[38:41]
	v_mfma_f32_16x16x32_bf16 v[28:31], v[162:165], v[220:223], v[28:31]
	v_mfma_f32_16x16x32_bf16 v[20:23], v[170:173], v[220:223], v[20:23]
	v_mfma_f32_16x16x32_bf16 v[12:15], v[162:165], v[238:241], v[12:15]
	v_mfma_f32_16x16x32_bf16 v[4:7], v[170:173], v[238:241], v[4:7]
	s_setprio 0
	s_setprio 1
	v_mfma_f32_16x16x32_bf16 v[58:61], v[174:177], v[190:193], 0
	v_mfma_f32_16x16x32_bf16 v[50:53], v[182:185], v[190:193], 0
	v_mfma_f32_16x16x32_bf16 v[42:45], v[174:177], v[208:211], 0
	v_mfma_f32_16x16x32_bf16 v[34:37], v[182:185], v[208:211], 0
	v_mfma_f32_16x16x32_bf16 v[24:27], v[174:177], v[216:219], 0
	v_mfma_f32_16x16x32_bf16 v[16:19], v[182:185], v[216:219], 0
	v_mfma_f32_16x16x32_bf16 v[8:11], v[174:177], v[224:227], 0
	v_mfma_f32_16x16x32_bf16 v[0:3], v[182:185], v[224:227], 0
	v_mfma_f32_16x16x32_bf16 v[58:61], v[178:181], v[204:207], v[58:61]
	v_mfma_f32_16x16x32_bf16 v[50:53], v[186:189], v[204:207], v[50:53]
	v_mfma_f32_16x16x32_bf16 v[42:45], v[178:181], v[212:215], v[42:45]
	v_mfma_f32_16x16x32_bf16 v[34:37], v[186:189], v[212:215], v[34:37]
	v_mfma_f32_16x16x32_bf16 v[24:27], v[178:181], v[220:223], v[24:27]
	v_mfma_f32_16x16x32_bf16 v[16:19], v[186:189], v[220:223], v[16:19]
	v_mfma_f32_16x16x32_bf16 v[8:11], v[178:181], v[238:241], v[8:11]
	v_mfma_f32_16x16x32_bf16 v[0:3], v[186:189], v[238:241], v[0:3]
	s_setprio 0
	s_barrier
	s_add_i32 s66, 0, 0x18000
	s_add_i32 s67, 0, 0x1c000
	v_add_u32_e32 v170, s66, v150
	v_add_u32_e32 v186, s67, v150
	ds_read_b128 v[144:147], v170
	ds_read_b128 v[162:165], v170 offset:1024
	ds_read_b128 v[166:169], v170 offset:2048
	ds_read_b128 v[170:173], v170 offset:3072
	ds_read_b128 v[174:177], v186
	ds_read_b128 v[178:181], v186 offset:1024
	ds_read_b128 v[182:185], v186 offset:2048
	ds_read_b128 v[186:189], v186 offset:3072
	s_add_u32 s50, s50, 0x40000
	s_addc_u32 s51, s51, 0
	s_mov_b32 m0, s52
	v_lshl_add_u64 v[248:249], s[50:51], 0, v[136:137]
	ds_read_b128 v[190:193], v161 offset:32768
	ds_read_b128 v[204:207], v161 offset:33792
	ds_read_b128 v[208:211], v161 offset:34816
	ds_read_b128 v[212:215], v161 offset:35840
	ds_read_b128 v[216:219], v161 offset:36864
	ds_read_b128 v[220:223], v161 offset:37888
	ds_read_b128 v[224:227], v161 offset:38912
	ds_read_b128 v[238:241], v161 offset:39936
	global_load_lds_dwordx4 v[248:249], off
	v_lshl_add_u64 v[248:249], s[50:51], 0, v[132:133]
	s_mov_b32 m0, s53
	s_nop 0
	global_load_lds_dwordx4 v[248:249], off
	s_waitcnt vmcnt(8)
	s_waitcnt lgkmcnt(0)
	s_barrier
	s_setprio 1
	s_waitcnt lgkmcnt(0)
	v_mfma_f32_16x16x32_bf16 v[126:129], v[144:147], v[190:193], v[126:129]
	v_mfma_f32_16x16x32_bf16 v[118:121], v[166:169], v[190:193], v[118:121]
	v_mfma_f32_16x16x32_bf16 v[110:113], v[144:147], v[208:211], v[110:113]
	v_mfma_f32_16x16x32_bf16 v[102:105], v[166:169], v[208:211], v[102:105]
	v_mfma_f32_16x16x32_bf16 v[94:97], v[144:147], v[216:219], v[94:97]
	v_mfma_f32_16x16x32_bf16 v[86:89], v[166:169], v[216:219], v[86:89]
	v_mfma_f32_16x16x32_bf16 v[78:81], v[144:147], v[224:227], v[78:81]
	v_mfma_f32_16x16x32_bf16 v[70:73], v[166:169], v[224:227], v[70:73]
	v_mfma_f32_16x16x32_bf16 v[126:129], v[162:165], v[204:207], v[126:129]
	v_mfma_f32_16x16x32_bf16 v[118:121], v[170:173], v[204:207], v[118:121]
	v_mfma_f32_16x16x32_bf16 v[110:113], v[162:165], v[212:215], v[110:113]
	v_mfma_f32_16x16x32_bf16 v[102:105], v[170:173], v[212:215], v[102:105]
	v_mfma_f32_16x16x32_bf16 v[94:97], v[162:165], v[220:223], v[94:97]
	v_mfma_f32_16x16x32_bf16 v[86:89], v[170:173], v[220:223], v[86:89]
	v_mfma_f32_16x16x32_bf16 v[78:81], v[162:165], v[238:241], v[78:81]
	v_mfma_f32_16x16x32_bf16 v[70:73], v[170:173], v[238:241], v[70:73]
	s_setprio 0
	s_setprio 1
	v_mfma_f32_16x16x32_bf16 v[122:125], v[174:177], v[190:193], v[122:125]
	v_mfma_f32_16x16x32_bf16 v[114:117], v[182:185], v[190:193], v[114:117]
	v_mfma_f32_16x16x32_bf16 v[106:109], v[174:177], v[208:211], v[106:109]
	v_mfma_f32_16x16x32_bf16 v[98:101], v[182:185], v[208:211], v[98:101]
	v_mfma_f32_16x16x32_bf16 v[90:93], v[174:177], v[216:219], v[90:93]
	v_mfma_f32_16x16x32_bf16 v[82:85], v[182:185], v[216:219], v[82:85]
	v_mfma_f32_16x16x32_bf16 v[74:77], v[174:177], v[224:227], v[74:77]
	v_mfma_f32_16x16x32_bf16 v[66:69], v[182:185], v[224:227], v[66:69]
	v_mfma_f32_16x16x32_bf16 v[122:125], v[178:181], v[204:207], v[122:125]
	v_mfma_f32_16x16x32_bf16 v[114:117], v[186:189], v[204:207], v[114:117]
	v_mfma_f32_16x16x32_bf16 v[106:109], v[178:181], v[212:215], v[106:109]
	v_mfma_f32_16x16x32_bf16 v[98:101], v[186:189], v[212:215], v[98:101]
	v_mfma_f32_16x16x32_bf16 v[90:93], v[178:181], v[220:223], v[90:93]
	v_mfma_f32_16x16x32_bf16 v[82:85], v[186:189], v[220:223], v[82:85]
	v_mfma_f32_16x16x32_bf16 v[74:77], v[178:181], v[238:241], v[74:77]
	v_mfma_f32_16x16x32_bf16 v[66:69], v[186:189], v[238:241], v[66:69]
	s_setprio 0
	s_barrier
; #define PG8_STAGE(bufoff, gbase, voff) do { _Pragma("unroll") for (int _i = 0; _i < 2; ++_i) \
;         __builtin_amdgcn_global_load_lds((const unsigned*)((const char*)(gbase) + (voff)[_i]), (PG8_LAS unsigned*)(lds + (bufoff) + ldsw + _i * 8192), 16, 0, 0); } while (0)
; #define PG8_LDA(dst, b, h) do { _Pragma("unroll") for (int m = 0; m < 4; ++m) _Pragma("unroll") for (int k = 0; k < 2; ++k) dst[m][k] = *(const PG8_LAS bf16x8*)(lds + PG8_SA(b, h) + aoff + m * 2048 + k * 1024); } while (0)
; #define PG8_LDB(dst, b, h) do { _Pragma("unroll") for (int n = 0; n < 2; ++n) _Pragma("unroll") for (int k = 0; k < 2; ++k) dst[n][k] = *(const PG8_LAS bf16x8*)(lds + PG8_SB(b, h) + boff + n * 2048 + k * 1024); } while (0)
; #define PG8_MMA(ai, bj, At, Bt) do { __builtin_amdgcn_s_setprio(1); _Pragma("unroll") for (int m = 0; m < 4; ++m) _Pragma("unroll") for (int n = 0; n < 2; ++n) _Pragma("unroll") for (int k = 0; k < 2; ++k) \
;         acc[ai][bj][m][n] = __builtin_amdgcn_mfma_f32_16x16x32_bf16(Bt[n][k], At[m][k], acc[ai][bj][m][n], 0, 0, 0); __builtin_amdgcn_s_setprio(0); } while (0)
; #define PG8_WAIT_V(n) asm volatile("s_waitcnt vmcnt(" #n ")" ::: "memory")
; #define PG8_WAIT_L(n) asm volatile("s_waitcnt lgkmcnt(" #n ")" ::: "memory")
; #define PG8_BAR __builtin_amdgcn_s_barrier()
; #define PG8_SCHED __builtin_amdgcn_sched_barrier(0)
; template <class Epi, class Sched, bool ALIGN_EPI = false, bool SP2 = false>
; __device__ __forceinline__ void gemm_phase(PG8_LAS unsigned char* lds, const Gemm g, const Sched& S, const Epi& E) {
;     ...
;         for (int t = 0; t < nt; t += 2) {
;     ...
;             if constexpr (SP2) {
;             PG8_LDB(B0, 0, 0); PG8_LDB(B1, 0, 1); PG8_SCHED; PG8_LDA(At, 0, 0); PG8_STAGE(PG8_SA(1, 1), a1 + hstep, voffA);
;             PG8_WAIT_V(8); PG8_WAIT_L(0); PG8_BAR; PG8_MMA(0, 0, At, B0); PG8_MMA(0, 1, At, B1); PG8_BAR; PG8_SCHED;
;     ...
;             PG8_WAIT_V(8); PG8_WAIT_L(0); PG8_BAR; PG8_MMA(0, 0, At, B0); PG8_MMA(0, 1, At, B1); PG8_BAR; PG8_SCHED;
;             PG8_LDA(At, 1, 1); PG8_STAGE(PG8_SB(1, 0), b3, voffB); PG8_STAGE(PG8_SB(1, 1), b3 + hstep, voffB); PG8_STAGE(PG8_SA(1, 0), a3, voffA);
;             PG8_WAIT_V(8); PG8_WAIT_L(0); PG8_BAR; PG8_MMA(1, 0, At, B0); PG8_MMA(1, 1, At, B1); PG8_BAR; PG8_SCHED;
	s_add_i32 s50, s66, s56
	v_lshl_add_u64 v[148:149], v[148:149], 0, s[8:9]
	s_mov_b32 m0, s50
	ds_read_b128 v[190:193], v161 offset:49152
	ds_read_b128 v[204:207], v161 offset:50176
	ds_read_b128 v[208:211], v161 offset:51200
	ds_read_b128 v[212:215], v161 offset:52224
	ds_read_b128 v[216:219], v161 offset:53248
	ds_read_b128 v[220:223], v161 offset:54272
	ds_read_b128 v[224:227], v161 offset:55296
	ds_read_b128 v[238:241], v161 offset:56320
	global_load_lds_dwordx4 v[148:149], off
	s_add_i32 m0, s50, 0x2000
	s_add_u32 s36, s36, 0x40080
	v_lshl_add_u64 v[148:149], v[242:243], 0, s[8:9]
	s_addc_u32 s37, s37, 0
	s_add_i32 s50, s67, s56
	global_load_lds_dwordx4 v[148:149], off
	v_lshl_add_u64 v[148:149], s[36:37], 0, v[134:135]
	s_mov_b32 m0, s50
	s_nop 0
	global_load_lds_dwordx4 v[148:149], off
	v_lshl_add_u64 v[148:149], s[36:37], 0, v[130:131]
	s_add_i32 m0, s50, 0x2000
	s_nop 0
	global_load_lds_dwordx4 v[148:149], off
	v_lshl_add_u64 v[148:149], v[244:245], 0, s[8:9]
	s_mov_b32 m0, s58
	s_nop 0
	global_load_lds_dwordx4 v[148:149], off
	v_lshl_add_u64 v[148:149], v[246:247], 0, s[8:9]
	s_mov_b32 m0, s59
	s_nop 0
	global_load_lds_dwordx4 v[148:149], off
	s_waitcnt vmcnt(8)
	s_waitcnt lgkmcnt(0)
	s_barrier
	s_setprio 1
	s_waitcnt lgkmcnt(0)
	v_mfma_f32_16x16x32_bf16 v[62:65], v[144:147], v[190:193], v[62:65]
	v_mfma_f32_16x16x32_bf16 v[54:57], v[166:169], v[190:193], v[54:57]
	v_mfma_f32_16x16x32_bf16 v[46:49], v[144:147], v[208:211], v[46:49]
	v_mfma_f32_16x16x32_bf16 v[38:41], v[166:169], v[208:211], v[38:41]
	v_mfma_f32_16x16x32_bf16 v[28:31], v[144:147], v[216:219], v[28:31]
	v_mfma_f32_16x16x32_bf16 v[20:23], v[166:169], v[216:219], v[20:23]
	v_mfma_f32_16x16x32_bf16 v[12:15], v[144:147], v[224:227], v[12:15]
	v_mfma_f32_16x16x32_bf16 v[4:7], v[166:169], v[224:227], v[4:7]
	v_mfma_f32_16x16x32_bf16 v[62:65], v[162:165], v[204:207], v[62:65]
	v_mfma_f32_16x16x32_bf16 v[54:57], v[170:173], v[204:207], v[54:57]
	v_mfma_f32_16x16x32_bf16 v[46:49], v[162:165], v[212:215], v[46:49]
	v_mfma_f32_16x16x32_bf16 v[38:41], v[170:173], v[212:215], v[38:41]
	v_mfma_f32_16x16x32_bf16 v[28:31], v[162:165], v[220:223], v[28:31]
	v_mfma_f32_16x16x32_bf16 v[20:23], v[170:173], v[220:223], v[20:23]
	v_mfma_f32_16x16x32_bf16 v[12:15], v[162:165], v[238:241], v[12:15]
	v_mfma_f32_16x16x32_bf16 v[4:7], v[170:173], v[238:241], v[4:7]
	s_setprio 0
	s_setprio 1
	v_mfma_f32_16x16x32_bf16 v[58:61], v[174:177], v[190:193], v[58:61]
	v_mfma_f32_16x16x32_bf16 v[50:53], v[182:185], v[190:193], v[50:53]
	v_mfma_f32_16x16x32_bf16 v[42:45], v[174:177], v[208:211], v[42:45]
	v_mfma_f32_16x16x32_bf16 v[34:37], v[182:185], v[208:211], v[34:37]
	v_mfma_f32_16x16x32_bf16 v[24:27], v[174:177], v[216:219], v[24:27]
	v_mfma_f32_16x16x32_bf16 v[16:19], v[182:185], v[216:219], v[16:19]
	v_mfma_f32_16x16x32_bf16 v[8:11], v[174:177], v[224:227], v[8:11]
	v_mfma_f32_16x16x32_bf16 v[0:3], v[182:185], v[224:227], v[0:3]
	v_mfma_f32_16x16x32_bf16 v[58:61], v[178:181], v[204:207], v[58:61]
	v_mfma_f32_16x16x32_bf16 v[50:53], v[186:189], v[204:207], v[50:53]
	v_mfma_f32_16x16x32_bf16 v[42:45], v[178:181], v[212:215], v[42:45]
	v_mfma_f32_16x16x32_bf16 v[34:37], v[186:189], v[212:215], v[34:37]
	v_mfma_f32_16x16x32_bf16 v[24:27], v[178:181], v[220:223], v[24:27]
	v_mfma_f32_16x16x32_bf16 v[16:19], v[186:189], v[220:223], v[16:19]
	v_mfma_f32_16x16x32_bf16 v[8:11], v[178:181], v[238:241], v[8:11]
	v_mfma_f32_16x16x32_bf16 v[0:3], v[186:189], v[238:241], v[0:3]
	s_setprio 0
	s_barrier
	s_add_i32 s91, s91, 2
	s_add_u32 vcc_lo, vcc_lo, 0x100
	s_addc_u32 vcc_hi, vcc_hi, 0
	s_add_u32 s64, s64, 0x100
	s_addc_u32 s65, s65, 0
	s_cmp_gt_u32 s91, 13
	s_cbranch_scc1 .Lgx1
.LBB0_549:
	s_add_u32 s36, vcc_lo, 0xfffc0080
	s_addc_u32 s37, vcc_hi, -1
	s_add_i32 s66, 0, 0x10000
	s_cmp_eq_u32 s91, 12
	s_cselect_b32 s51, s35, s37
	s_cselect_b32 s50, s62, s36
	v_add_u32_e32 v148, s66, v150
	s_cselect_b32 s37, s43, s65
	s_cselect_b32 s36, s63, s64
	s_add_i32 s68, 0, 0x14000
	ds_read_b128 v[144:147], v148
	ds_read_b128 v[162:165], v148 offset:1024
	ds_read_b128 v[166:169], v148 offset:2048
	ds_read_b128 v[170:173], v148 offset:3072
	v_add_u32_e32 v148, s68, v150
	ds_read_b128 v[174:177], v148
	ds_read_b128 v[178:181], v148 offset:1024
	ds_read_b128 v[182:185], v148 offset:2048
	ds_read_b128 v[186:189], v148 offset:3072
	v_lshl_add_u64 v[148:149], vcc, 0, v[140:141]
	s_add_i32 m0, s4, 0xc000
	ds_read_b128 v[190:193], v161
	ds_read_b128 v[204:207], v161 offset:1024
	ds_read_b128 v[208:211], v161 offset:2048
	ds_read_b128 v[212:215], v161 offset:3072
	ds_read_b128 v[216:219], v161 offset:4096
	ds_read_b128 v[220:223], v161 offset:5120
	ds_read_b128 v[224:227], v161 offset:6144
	ds_read_b128 v[238:241], v161 offset:7168
	global_load_lds_dwordx4 v[148:149], off
	v_lshl_add_u64 v[148:149], vcc, 0, v[142:143]
	s_add_i32 m0, s4, 0xe000
	s_nop 0
	global_load_lds_dwordx4 v[148:149], off
	s_waitcnt vmcnt(8)
	s_waitcnt lgkmcnt(0)
	s_barrier
; #define PG8_STAGE(bufoff, gbase, voff) do { _Pragma("unroll") for (int _i = 0; _i < 2; ++_i) \
;         __builtin_amdgcn_global_load_lds((const unsigned*)((const char*)(gbase) + (voff)[_i]), (PG8_LAS unsigned*)(lds + (bufoff) + ldsw + _i * 8192), 16, 0, 0); } while (0)
; #define PG8_LDA(dst, b, h) do { _Pragma("unroll") for (int m = 0; m < 4; ++m) _Pragma("unroll") for (int k = 0; k < 2; ++k) dst[m][k] = *(const PG8_LAS bf16x8*)(lds + PG8_SA(b, h) + aoff + m * 2048 + k * 1024); } while (0)
; #define PG8_LDB(dst, b, h) do { _Pragma("unroll") for (int n = 0; n < 2; ++n) _Pragma("unroll") for (int k = 0; k < 2; ++k) dst[n][k] = *(const PG8_LAS bf16x8*)(lds + PG8_SB(b, h) + boff + n * 2048 + k * 1024); } while (0)
; #define PG8_MMA(ai, bj, At, Bt) do { __builtin_amdgcn_s_setprio(1); _Pragma("unroll") for (int m = 0; m < 4; ++m) _Pragma("unroll") for (int n = 0; n < 2; ++n) _Pragma("unroll") for (int k = 0; k < 2; ++k) \
;         acc[ai][bj][m][n] = __builtin_amdgcn_mfma_f32_16x16x32_bf16(Bt[n][k], At[m][k], acc[ai][bj][m][n], 0, 0, 0); __builtin_amdgcn_s_setprio(0); } while (0)
; #define PG8_WAIT_V(n) asm volatile("s_waitcnt vmcnt(" #n ")" ::: "memory")
; #define PG8_WAIT_L(n) asm volatile("s_waitcnt lgkmcnt(" #n ")" ::: "memory")
; #define PG8_BAR __builtin_amdgcn_s_barrier()
; #define PG8_SCHED __builtin_amdgcn_sched_barrier(0)
; template <class Epi, class Sched, bool ALIGN_EPI = false, bool SP2 = false>
; __device__ __forceinline__ void gemm_phase(PG8_LAS unsigned char* lds, const Gemm g, const Sched& S, const Epi& E) {
;     ...
;             if constexpr (SP2) {
;             PG8_LDB(B0, 0, 0); PG8_LDB(B1, 0, 1); PG8_SCHED; PG8_LDA(At, 0, 0); PG8_STAGE(PG8_SA(1, 1), a1 + hstep, voffA);
;             PG8_WAIT_V(8); PG8_WAIT_L(0); PG8_BAR; PG8_MMA(0, 0, At, B0); PG8_MMA(0, 1, At, B1); PG8_BAR; PG8_SCHED;
;             PG8_LDA(At, 0, 1); PG8_STAGE(PG8_SB(0, 0), b2, voffB); PG8_STAGE(PG8_SB(0, 1), b2 + hstep, voffB); PG8_STAGE(PG8_SA(0, 0), a2, voffA);
;             PG8_WAIT_V(8); PG8_WAIT_L(0); PG8_BAR; PG8_MMA(1, 0, At, B0); PG8_MMA(1, 1, At, B1); PG8_BAR; PG8_SCHED;
;             PG8_LDB(B0, 1, 0); PG8_LDB(B1, 1, 1); PG8_SCHED; PG8_LDA(At, 1, 0); PG8_STAGE(PG8_SA(0, 1), a2 + hstep, voffA);
;             PG8_WAIT_V(8); PG8_WAIT_L(0); PG8_BAR; PG8_MMA(0, 0, At, B0); PG8_MMA(0, 1, At, B1); PG8_BAR; PG8_SCHED;
	s_setprio 1
	s_waitcnt lgkmcnt(0)
	v_mfma_f32_16x16x32_bf16 v[126:129], v[144:147], v[190:193], v[126:129]
	v_mfma_f32_16x16x32_bf16 v[118:121], v[166:169], v[190:193], v[118:121]
	v_mfma_f32_16x16x32_bf16 v[110:113], v[144:147], v[208:211], v[110:113]
	v_mfma_f32_16x16x32_bf16 v[102:105], v[166:169], v[208:211], v[102:105]
	v_mfma_f32_16x16x32_bf16 v[94:97], v[144:147], v[216:219], v[94:97]
	v_mfma_f32_16x16x32_bf16 v[86:89], v[166:169], v[216:219], v[86:89]
	v_mfma_f32_16x16x32_bf16 v[78:81], v[144:147], v[224:227], v[78:81]
	v_mfma_f32_16x16x32_bf16 v[70:73], v[166:169], v[224:227], v[70:73]
	v_mfma_f32_16x16x32_bf16 v[126:129], v[162:165], v[204:207], v[126:129]
	v_mfma_f32_16x16x32_bf16 v[118:121], v[170:173], v[204:207], v[118:121]
	v_mfma_f32_16x16x32_bf16 v[110:113], v[162:165], v[212:215], v[110:113]
	v_mfma_f32_16x16x32_bf16 v[102:105], v[170:173], v[212:215], v[102:105]
	v_mfma_f32_16x16x32_bf16 v[94:97], v[162:165], v[220:223], v[94:97]
	v_mfma_f32_16x16x32_bf16 v[86:89], v[170:173], v[220:223], v[86:89]
	v_mfma_f32_16x16x32_bf16 v[78:81], v[162:165], v[238:241], v[78:81]
	v_mfma_f32_16x16x32_bf16 v[70:73], v[170:173], v[238:241], v[70:73]
	s_setprio 0
	s_setprio 1
	v_mfma_f32_16x16x32_bf16 v[122:125], v[174:177], v[190:193], v[122:125]
	v_mfma_f32_16x16x32_bf16 v[114:117], v[182:185], v[190:193], v[114:117]
	v_mfma_f32_16x16x32_bf16 v[106:109], v[174:177], v[208:211], v[106:109]
	v_mfma_f32_16x16x32_bf16 v[98:101], v[182:185], v[208:211], v[98:101]
	v_mfma_f32_16x16x32_bf16 v[90:93], v[174:177], v[216:219], v[90:93]
	v_mfma_f32_16x16x32_bf16 v[82:85], v[182:185], v[216:219], v[82:85]
	v_mfma_f32_16x16x32_bf16 v[74:77], v[174:177], v[224:227], v[74:77]
	v_mfma_f32_16x16x32_bf16 v[66:69], v[182:185], v[224:227], v[66:69]
	v_mfma_f32_16x16x32_bf16 v[122:125], v[178:181], v[204:207], v[122:125]
	v_mfma_f32_16x16x32_bf16 v[114:117], v[186:189], v[204:207], v[114:117]
	v_mfma_f32_16x16x32_bf16 v[106:109], v[178:181], v[212:215], v[106:109]
	v_mfma_f32_16x16x32_bf16 v[98:101], v[186:189], v[212:215], v[98:101]
	v_mfma_f32_16x16x32_bf16 v[90:93], v[178:181], v[220:223], v[90:93]
	v_mfma_f32_16x16x32_bf16 v[82:85], v[186:189], v[220:223], v[82:85]
	v_mfma_f32_16x16x32_bf16 v[74:77], v[178:181], v[238:241], v[74:77]
	v_mfma_f32_16x16x32_bf16 v[66:69], v[186:189], v[238:241], v[66:69]
	s_setprio 0
	s_barrier
	s_add_i32 s66, s66, s56
	v_lshl_add_u64 v[148:149], s[36:37], 0, v[134:135]
	s_mov_b32 m0, s66
	ds_read_b128 v[190:193], v161 offset:16384
	ds_read_b128 v[204:207], v161 offset:17408
	ds_read_b128 v[208:211], v161 offset:18432
	ds_read_b128 v[212:215], v161 offset:19456
	ds_read_b128 v[216:219], v161 offset:20480
	ds_read_b128 v[220:223], v161 offset:21504
	ds_read_b128 v[224:227], v161 offset:22528
	ds_read_b128 v[238:241], v161 offset:23552
	global_load_lds_dwordx4 v[148:149], off
	s_add_i32 m0, s66, 0x2000
	s_add_u32 s66, s36, 0x40000
	v_lshl_add_u64 v[242:243], s[36:37], 0, v[130:131]
	s_addc_u32 s67, s37, 0
	s_add_i32 s68, s68, s56
	global_load_lds_dwordx4 v[242:243], off
	v_lshl_add_u64 v[244:245], s[66:67], 0, v[134:135]
	s_mov_b32 m0, s68
	v_lshl_add_u64 v[246:247], s[50:51], 0, v[132:133]
	global_load_lds_dwordx4 v[244:245], off
	v_lshl_add_u64 v[244:245], s[66:67], 0, v[130:131]
	s_add_i32 m0, s68, 0x2000
	s_nop 0
	global_load_lds_dwordx4 v[244:245], off
	v_lshl_add_u64 v[244:245], s[50:51], 0, v[136:137]
	s_mov_b32 m0, s4
	s_nop 0
	global_load_lds_dwordx4 v[244:245], off
	s_mov_b32 m0, s5
	s_nop 0
	global_load_lds_dwordx4 v[246:247], off
	s_waitcnt vmcnt(8)
	s_waitcnt lgkmcnt(0)
	s_barrier
	s_setprio 1
	s_waitcnt lgkmcnt(0)
	v_mfma_f32_16x16x32_bf16 v[62:65], v[144:147], v[190:193], v[62:65]
	v_mfma_f32_16x16x32_bf16 v[54:57], v[166:169], v[190:193], v[54:57]
	v_mfma_f32_16x16x32_bf16 v[46:49], v[144:147], v[208:211], v[46:49]
	v_mfma_f32_16x16x32_bf16 v[38:41], v[166:169], v[208:211], v[38:41]
	v_mfma_f32_16x16x32_bf16 v[28:31], v[144:147], v[216:219], v[28:31]
	v_mfma_f32_16x16x32_bf16 v[20:23], v[166:169], v[216:219], v[20:23]
	v_mfma_f32_16x16x32_bf16 v[12:15], v[144:147], v[224:227], v[12:15]
	v_mfma_f32_16x16x32_bf16 v[4:7], v[166:169], v[224:227], v[4:7]
	v_mfma_f32_16x16x32_bf16 v[62:65], v[162:165], v[204:207], v[62:65]
	v_mfma_f32_16x16x32_bf16 v[54:57], v[170:173], v[204:207], v[54:57]
	v_mfma_f32_16x16x32_bf16 v[46:49], v[162:165], v[212:215], v[46:49]
	v_mfma_f32_16x16x32_bf16 v[38:41], v[170:173], v[212:215], v[38:41]
	v_mfma_f32_16x16x32_bf16 v[28:31], v[162:165], v[220:223], v[28:31]
	v_mfma_f32_16x16x32_bf16 v[20:23], v[170:173], v[220:223], v[20:23]
	v_mfma_f32_16x16x32_bf16 v[12:15], v[162:165], v[238:241], v[12:15]
	v_mfma_f32_16x16x32_bf16 v[4:7], v[170:173], v[238:241], v[4:7]
	s_setprio 0
	s_setprio 1
	v_mfma_f32_16x16x32_bf16 v[58:61], v[174:177], v[190:193], v[58:61]
	v_mfma_f32_16x16x32_bf16 v[50:53], v[182:185], v[190:193], v[50:53]
	v_mfma_f32_16x16x32_bf16 v[42:45], v[174:177], v[208:211], v[42:45]
	v_mfma_f32_16x16x32_bf16 v[34:37], v[182:185], v[208:211], v[34:37]
	v_mfma_f32_16x16x32_bf16 v[24:27], v[174:177], v[216:219], v[24:27]
	v_mfma_f32_16x16x32_bf16 v[16:19], v[182:185], v[216:219], v[16:19]
	v_mfma_f32_16x16x32_bf16 v[8:11], v[174:177], v[224:227], v[8:11]
	v_mfma_f32_16x16x32_bf16 v[0:3], v[182:185], v[224:227], v[0:3]
	v_mfma_f32_16x16x32_bf16 v[58:61], v[178:181], v[204:207], v[58:61]
	v_mfma_f32_16x16x32_bf16 v[50:53], v[186:189], v[204:207], v[50:53]
	v_mfma_f32_16x16x32_bf16 v[42:45], v[178:181], v[212:215], v[42:45]
	v_mfma_f32_16x16x32_bf16 v[34:37], v[186:189], v[212:215], v[34:37]
	v_mfma_f32_16x16x32_bf16 v[24:27], v[178:181], v[220:223], v[24:27]
	v_mfma_f32_16x16x32_bf16 v[16:19], v[186:189], v[220:223], v[16:19]
	v_mfma_f32_16x16x32_bf16 v[8:11], v[178:181], v[238:241], v[8:11]
	v_mfma_f32_16x16x32_bf16 v[0:3], v[186:189], v[238:241], v[0:3]
	s_setprio 0
	s_barrier
; #define PG8_STAGE(bufoff, gbase, voff) do { _Pragma("unroll") for (int _i = 0; _i < 2; ++_i) \
;         __builtin_amdgcn_global_load_lds((const unsigned*)((const char*)(gbase) + (voff)[_i]), (PG8_LAS unsigned*)(lds + (bufoff) + ldsw + _i * 8192), 16, 0, 0); } while (0)
; #define PG8_LDA(dst, b, h) do { _Pragma("unroll") for (int m = 0; m < 4; ++m) _Pragma("unroll") for (int k = 0; k < 2; ++k) dst[m][k] = *(const PG8_LAS bf16x8*)(lds + PG8_SA(b, h) + aoff + m * 2048 + k * 1024); } while (0)
; #define PG8_LDB(dst, b, h) do { _Pragma("unroll") for (int n = 0; n < 2; ++n) _Pragma("unroll") for (int k = 0; k < 2; ++k) dst[n][k] = *(const PG8_LAS bf16x8*)(lds + PG8_SB(b, h) + boff + n * 2048 + k * 1024); } while (0)
; #define PG8_MMA(ai, bj, At, Bt) do { __builtin_amdgcn_s_setprio(1); _Pragma("unroll") for (int m = 0; m < 4; ++m) _Pragma("unroll") for (int n = 0; n < 2; ++n) _Pragma("unroll") for (int k = 0; k < 2; ++k) \
;         acc[ai][bj][m][n] = __builtin_amdgcn_mfma_f32_16x16x32_bf16(Bt[n][k], At[m][k], acc[ai][bj][m][n], 0, 0, 0); __builtin_amdgcn_s_setprio(0); } while (0)
; #define PG8_WAIT_V(n) asm volatile("s_waitcnt vmcnt(" #n ")" ::: "memory")
; #define PG8_WAIT_L(n) asm volatile("s_waitcnt lgkmcnt(" #n ")" ::: "memory")
; #define PG8_BAR __builtin_amdgcn_s_barrier()
; #define PG8_SCHED __builtin_amdgcn_sched_barrier(0)
; template <class Epi, class Sched, bool ALIGN_EPI = false, bool SP2 = false>
; __device__ __forceinline__ void gemm_phase(PG8_LAS unsigned char* lds, const Gemm g, const Sched& S, const Epi& E) {
;     ...
;             PG8_WAIT_V(8); PG8_WAIT_L(0); PG8_BAR; PG8_MMA(1, 0, At, B0); PG8_MMA(1, 1, At, B1); PG8_BAR; PG8_SCHED;
;             PG8_LDB(B0, 1, 0); PG8_LDB(B1, 1, 1); PG8_SCHED; PG8_LDA(At, 1, 0); PG8_STAGE(PG8_SA(0, 1), a2 + hstep, voffA);
;             PG8_WAIT_V(8); PG8_WAIT_L(0); PG8_BAR; PG8_MMA(0, 0, At, B0); PG8_MMA(0, 1, At, B1); PG8_BAR; PG8_SCHED;
	s_add_i32 s66, 0, 0x18000
	s_add_i32 s67, 0, 0x1c000
	v_add_u32_e32 v170, s66, v150
	v_add_u32_e32 v186, s67, v150
	ds_read_b128 v[144:147], v170
	ds_read_b128 v[162:165], v170 offset:1024
	ds_read_b128 v[166:169], v170 offset:2048
	ds_read_b128 v[170:173], v170 offset:3072
	ds_read_b128 v[174:177], v186
	ds_read_b128 v[178:181], v186 offset:1024
	ds_read_b128 v[182:185], v186 offset:2048
	ds_read_b128 v[186:189], v186 offset:3072
	s_add_u32 s50, s50, 0x40000
	s_addc_u32 s51, s51, 0
	s_mov_b32 m0, s52
	v_lshl_add_u64 v[248:249], s[50:51], 0, v[136:137]
	ds_read_b128 v[190:193], v161 offset:32768
	ds_read_b128 v[204:207], v161 offset:33792
	ds_read_b128 v[208:211], v161 offset:34816
	ds_read_b128 v[212:215], v161 offset:35840
	ds_read_b128 v[216:219], v161 offset:36864
	ds_read_b128 v[220:223], v161 offset:37888
	ds_read_b128 v[224:227], v161 offset:38912
	ds_read_b128 v[238:241], v161 offset:39936
	global_load_lds_dwordx4 v[248:249], off
	v_lshl_add_u64 v[248:249], s[50:51], 0, v[132:133]
	s_mov_b32 m0, s53
	s_nop 0
	global_load_lds_dwordx4 v[248:249], off
	s_waitcnt vmcnt(8)
	s_waitcnt lgkmcnt(0)
	s_barrier
	s_setprio 1
	s_waitcnt lgkmcnt(0)
	v_mfma_f32_16x16x32_bf16 v[126:129], v[144:147], v[190:193], v[126:129]
	v_mfma_f32_16x16x32_bf16 v[118:121], v[166:169], v[190:193], v[118:121]
	v_mfma_f32_16x16x32_bf16 v[110:113], v[144:147], v[208:211], v[110:113]
	v_mfma_f32_16x16x32_bf16 v[102:105], v[166:169], v[208:211], v[102:105]
	v_mfma_f32_16x16x32_bf16 v[94:97], v[144:147], v[216:219], v[94:97]
	v_mfma_f32_16x16x32_bf16 v[86:89], v[166:169], v[216:219], v[86:89]
	v_mfma_f32_16x16x32_bf16 v[78:81], v[144:147], v[224:227], v[78:81]
	v_mfma_f32_16x16x32_bf16 v[70:73], v[166:169], v[224:227], v[70:73]
	v_mfma_f32_16x16x32_bf16 v[126:129], v[162:165], v[204:207], v[126:129]
	v_mfma_f32_16x16x32_bf16 v[118:121], v[170:173], v[204:207], v[118:121]
	v_mfma_f32_16x16x32_bf16 v[110:113], v[162:165], v[212:215], v[110:113]
	v_mfma_f32_16x16x32_bf16 v[102:105], v[170:173], v[212:215], v[102:105]
	v_mfma_f32_16x16x32_bf16 v[94:97], v[162:165], v[220:223], v[94:97]
	v_mfma_f32_16x16x32_bf16 v[86:89], v[170:173], v[220:223], v[86:89]
	v_mfma_f32_16x16x32_bf16 v[78:81], v[162:165], v[238:241], v[78:81]
	v_mfma_f32_16x16x32_bf16 v[70:73], v[170:173], v[238:241], v[70:73]
	s_setprio 0
	s_setprio 1
	v_mfma_f32_16x16x32_bf16 v[122:125], v[174:177], v[190:193], v[122:125]
	v_mfma_f32_16x16x32_bf16 v[114:117], v[182:185], v[190:193], v[114:117]
	v_mfma_f32_16x16x32_bf16 v[106:109], v[174:177], v[208:211], v[106:109]
	v_mfma_f32_16x16x32_bf16 v[98:101], v[182:185], v[208:211], v[98:101]
	v_mfma_f32_16x16x32_bf16 v[90:93], v[174:177], v[216:219], v[90:93]
	v_mfma_f32_16x16x32_bf16 v[82:85], v[182:185], v[216:219], v[82:85]
	v_mfma_f32_16x16x32_bf16 v[74:77], v[174:177], v[224:227], v[74:77]
	v_mfma_f32_16x16x32_bf16 v[66:69], v[182:185], v[224:227], v[66:69]
	v_mfma_f32_16x16x32_bf16 v[122:125], v[178:181], v[204:207], v[122:125]
	v_mfma_f32_16x16x32_bf16 v[114:117], v[186:189], v[204:207], v[114:117]
	v_mfma_f32_16x16x32_bf16 v[106:109], v[178:181], v[212:215], v[106:109]
	v_mfma_f32_16x16x32_bf16 v[98:101], v[186:189], v[212:215], v[98:101]
	v_mfma_f32_16x16x32_bf16 v[90:93], v[178:181], v[220:223], v[90:93]
	v_mfma_f32_16x16x32_bf16 v[82:85], v[186:189], v[220:223], v[82:85]
	v_mfma_f32_16x16x32_bf16 v[74:77], v[178:181], v[238:241], v[74:77]
	v_mfma_f32_16x16x32_bf16 v[66:69], v[186:189], v[238:241], v[66:69]
	s_setprio 0
	s_barrier
; #define PG8_STAGE(bufoff, gbase, voff) do { _Pragma("unroll") for (int _i = 0; _i < 2; ++_i) \
;         __builtin_amdgcn_global_load_lds((const unsigned*)((const char*)(gbase) + (voff)[_i]), (PG8_LAS unsigned*)(lds + (bufoff) + ldsw + _i * 8192), 16, 0, 0); } while (0)
; #define PG8_LDA(dst, b, h) do { _Pragma("unroll") for (int m = 0; m < 4; ++m) _Pragma("unroll") for (int k = 0; k < 2; ++k) dst[m][k] = *(const PG8_LAS bf16x8*)(lds + PG8_SA(b, h) + aoff + m * 2048 + k * 1024); } while (0)
; #define PG8_MMA(ai, bj, At, Bt) do { __builtin_amdgcn_s_setprio(1); _Pragma("unroll") for (int m = 0; m < 4; ++m) _Pragma("unroll") for (int n = 0; n < 2; ++n) _Pragma("unroll") for (int k = 0; k < 2; ++k) \
;         acc[ai][bj][m][n] = __builtin_amdgcn_mfma_f32_16x16x32_bf16(Bt[n][k], At[m][k], acc[ai][bj][m][n], 0, 0, 0); __builtin_amdgcn_s_setprio(0); } while (0)
; #define PG8_WAIT_V(n) asm volatile("s_waitcnt vmcnt(" #n ")" ::: "memory")
; #define PG8_WAIT_L(n) asm volatile("s_waitcnt lgkmcnt(" #n ")" ::: "memory")
; #define PG8_BAR __builtin_amdgcn_s_barrier()
; #define PG8_SCHED __builtin_amdgcn_sched_barrier(0)
; template <class Epi, class Sched, bool ALIGN_EPI = false, bool SP2 = false>
; __device__ __forceinline__ void gemm_phase(PG8_LAS unsigned char* lds, const Gemm g, const Sched& S, const Epi& E) {
;     ...
;         for (int t = 0; t < nt; t += 2) {
;     ...
;             PG8_WAIT_V(8); PG8_WAIT_L(0); PG8_BAR; PG8_MMA(0, 0, At, B0); PG8_MMA(0, 1, At, B1); PG8_BAR; PG8_SCHED;
;             PG8_LDA(At, 1, 1); PG8_STAGE(PG8_SB(1, 0), b3, voffB); PG8_STAGE(PG8_SB(1, 1), b3 + hstep, voffB); PG8_STAGE(PG8_SA(1, 0), a3, voffA);
;             PG8_WAIT_V(8); PG8_WAIT_L(0); PG8_BAR; PG8_MMA(1, 0, At, B0); PG8_MMA(1, 1, At, B1); PG8_BAR; PG8_SCHED;
;     ...
;         if constexpr (ALIGN_EPI) { if (wr == 0) PG8_BAR; }
	s_add_i32 s50, s66, s56
	v_lshl_add_u64 v[148:149], v[148:149], 0, s[8:9]
	s_mov_b32 m0, s50
	ds_read_b128 v[190:193], v161 offset:49152
	ds_read_b128 v[204:207], v161 offset:50176
	ds_read_b128 v[208:211], v161 offset:51200
	ds_read_b128 v[212:215], v161 offset:52224
	ds_read_b128 v[216:219], v161 offset:53248
	ds_read_b128 v[220:223], v161 offset:54272
	ds_read_b128 v[224:227], v161 offset:55296
	ds_read_b128 v[238:241], v161 offset:56320
	global_load_lds_dwordx4 v[148:149], off
	s_add_i32 m0, s50, 0x2000
	s_add_u32 s36, s36, 0x40080
	v_lshl_add_u64 v[148:149], v[242:243], 0, s[8:9]
	s_addc_u32 s37, s37, 0
	s_add_i32 s50, s67, s56
	global_load_lds_dwordx4 v[148:149], off
	v_lshl_add_u64 v[148:149], s[36:37], 0, v[134:135]
	s_mov_b32 m0, s50
	s_nop 0
	global_load_lds_dwordx4 v[148:149], off
	v_lshl_add_u64 v[148:149], s[36:37], 0, v[130:131]
	s_add_i32 m0, s50, 0x2000
	s_nop 0
	global_load_lds_dwordx4 v[148:149], off
	v_lshl_add_u64 v[148:149], v[244:245], 0, s[8:9]
	s_mov_b32 m0, s58
	s_nop 0
	global_load_lds_dwordx4 v[148:149], off
	v_lshl_add_u64 v[148:149], v[246:247], 0, s[8:9]
	s_mov_b32 m0, s59
	s_nop 0
	global_load_lds_dwordx4 v[148:149], off
	s_waitcnt vmcnt(8)
	s_waitcnt lgkmcnt(0)
	s_barrier
	s_setprio 1
	s_waitcnt lgkmcnt(0)
	v_mfma_f32_16x16x32_bf16 v[62:65], v[144:147], v[190:193], v[62:65]
	v_mfma_f32_16x16x32_bf16 v[54:57], v[166:169], v[190:193], v[54:57]
	v_mfma_f32_16x16x32_bf16 v[46:49], v[144:147], v[208:211], v[46:49]
	v_mfma_f32_16x16x32_bf16 v[38:41], v[166:169], v[208:211], v[38:41]
	v_mfma_f32_16x16x32_bf16 v[28:31], v[144:147], v[216:219], v[28:31]
	v_mfma_f32_16x16x32_bf16 v[20:23], v[166:169], v[216:219], v[20:23]
	v_mfma_f32_16x16x32_bf16 v[12:15], v[144:147], v[224:227], v[12:15]
	v_mfma_f32_16x16x32_bf16 v[4:7], v[166:169], v[224:227], v[4:7]
	v_mfma_f32_16x16x32_bf16 v[62:65], v[162:165], v[204:207], v[62:65]
	v_mfma_f32_16x16x32_bf16 v[54:57], v[170:173], v[204:207], v[54:57]
	v_mfma_f32_16x16x32_bf16 v[46:49], v[162:165], v[212:215], v[46:49]
	v_mfma_f32_16x16x32_bf16 v[38:41], v[170:173], v[212:215], v[38:41]
	v_mfma_f32_16x16x32_bf16 v[28:31], v[162:165], v[220:223], v[28:31]
	v_mfma_f32_16x16x32_bf16 v[20:23], v[170:173], v[220:223], v[20:23]
	v_mfma_f32_16x16x32_bf16 v[12:15], v[162:165], v[238:241], v[12:15]
	v_mfma_f32_16x16x32_bf16 v[4:7], v[170:173], v[238:241], v[4:7]
	s_setprio 0
	s_setprio 1
	v_mfma_f32_16x16x32_bf16 v[58:61], v[174:177], v[190:193], v[58:61]
	v_mfma_f32_16x16x32_bf16 v[50:53], v[182:185], v[190:193], v[50:53]
	v_mfma_f32_16x16x32_bf16 v[42:45], v[174:177], v[208:211], v[42:45]
	v_mfma_f32_16x16x32_bf16 v[34:37], v[182:185], v[208:211], v[34:37]
	v_mfma_f32_16x16x32_bf16 v[24:27], v[174:177], v[216:219], v[24:27]
	v_mfma_f32_16x16x32_bf16 v[16:19], v[182:185], v[216:219], v[16:19]
	v_mfma_f32_16x16x32_bf16 v[8:11], v[174:177], v[224:227], v[8:11]
	v_mfma_f32_16x16x32_bf16 v[0:3], v[182:185], v[224:227], v[0:3]
	v_mfma_f32_16x16x32_bf16 v[58:61], v[178:181], v[204:207], v[58:61]
	v_mfma_f32_16x16x32_bf16 v[50:53], v[186:189], v[204:207], v[50:53]
	v_mfma_f32_16x16x32_bf16 v[42:45], v[178:181], v[212:215], v[42:45]
	v_mfma_f32_16x16x32_bf16 v[34:37], v[186:189], v[212:215], v[34:37]
	v_mfma_f32_16x16x32_bf16 v[24:27], v[178:181], v[220:223], v[24:27]
	v_mfma_f32_16x16x32_bf16 v[16:19], v[186:189], v[220:223], v[16:19]
	v_mfma_f32_16x16x32_bf16 v[8:11], v[178:181], v[238:241], v[8:11]
	v_mfma_f32_16x16x32_bf16 v[0:3], v[186:189], v[238:241], v[0:3]
	s_setprio 0
	s_barrier
	s_add_i32 s91, s91, 2
	s_add_u32 vcc_lo, vcc_lo, 0x100
	s_addc_u32 vcc_hi, vcc_hi, 0
	s_add_u32 s64, s64, 0x100
	s_addc_u32 s65, s65, 0
	s_cmp_gt_u32 s91, 13
	s_cbranch_scc0 .LBB0_549
.Lgx1:
	s_and_b64 vcc, exec, s[30:31]
	s_cbranch_vccz .LBB0_552
	s_barrier

; #define PG8_STAGE(bufoff, gbase, voff) do { _Pragma("unroll") for (int _i = 0; _i < 2; ++_i) \
;         __builtin_amdgcn_global_load_lds((const unsigned*)((const char*)(gbase) + (voff)[_i]), (PG8_LAS unsigned*)(lds + (bufoff) + ldsw + _i * 8192), 16, 0, 0); } while (0)
; #define PG8_LDA(dst, b, h) do { _Pragma("unroll") for (int m = 0; m < 4; ++m) _Pragma("unroll") for (int k = 0; k < 2; ++k) dst[m][k] = *(const PG8_LAS bf16x8*)(lds + PG8_SA(b, h) + aoff + m * 2048 + k * 1024); } while (0)
; #define PG8_LDB(dst, b, h) do { _Pragma("unroll") for (int n = 0; n < 2; ++n) _Pragma("unroll") for (int k = 0; k < 2; ++k) dst[n][k] = *(const PG8_LAS bf16x8*)(lds + PG8_SB(b, h) + boff + n * 2048 + k * 1024); } while (0)
; #define PG8_WAIT_V(n) asm volatile("s_waitcnt vmcnt(" #n ")" ::: "memory")
; #define PG8_WAIT_L(n) asm volatile("s_waitcnt lgkmcnt(" #n ")" ::: "memory")
; #define PG8_BAR __builtin_amdgcn_s_barrier()
; #define PG8_SCHED __builtin_amdgcn_sched_barrier(0)
; template <class Epi, class Sched, bool ALIGN_EPI = false, bool SP2 = false>
; __device__ __forceinline__ void gemm_phase(PG8_LAS unsigned char* lds, const Gemm g, const Sched& S, const Epi& E) {
;     ...
;         const bool has_next = S.next(ui + 1, nxt);
;         const char* nA = has_next ? (const char*)g.A + (size_t)nxt.pm * tstep : cA; const char* nB = has_next ? (const char*)g.Bt + (size_t)nxt.pn * tstep : cB;
;         for (int t = 0; t < nt; t += 2) {
;             const bool last = (t == nt - 2);
;             const char* a1 = cA + (size_t)(t + 1) * kstep;
;             const char* a2 = last ? nA : cA + (size_t)(t + 2) * kstep; const char* b2 = last ? nB : cB + (size_t)(t + 2) * kstep;
;             const char* a3 = a2 + kstep; const char* b3 = b2 + kstep;
;             if (last && has_next) S.a_ready(nxt);
;             if constexpr (SP2) {
;             PG8_LDB(B0, 0, 0); PG8_LDB(B1, 0, 1); PG8_SCHED; PG8_LDA(At, 0, 0); PG8_STAGE(PG8_SA(1, 1), a1 + hstep, voffA);
;             PG8_WAIT_V(8); PG8_WAIT_L(0); PG8_BAR; PG8_MMA(0, 0, At, B0); PG8_MMA(0, 1, At, B1); PG8_BAR; PG8_SCHED;
;             PG8_LDA(At, 0, 1); PG8_STAGE(PG8_SB(0, 0), b2, voffB); PG8_STAGE(PG8_SB(0, 1), b2 + hstep, voffB); PG8_STAGE(PG8_SA(0, 0), a2, voffA);
;             PG8_WAIT_V(8); PG8_WAIT_L(0); PG8_BAR; PG8_MMA(1, 0, At, B0); PG8_MMA(1, 1, At, B1); PG8_BAR; PG8_SCHED;
.LBB0_935:
	s_ashr_i32 s27, s26, 31
	s_lshl_b64 s[28:29], s[26:27], 19
	s_add_u32 s28, s5, s28
	s_addc_u32 s29, s17, s29
	s_and_b64 s[30:31], s[40:41], exec
	s_cselect_b32 s27, s29, s37
	s_cselect_b32 s59, s28, s36
	s_ashr_i32 s25, s24, 31
	s_lshl_b64 s[30:31], s[24:25], 19
	s_add_u32 s30, s44, s30
	s_addc_u32 s31, s45, s31
	s_and_b64 s[46:47], s[40:41], exec
	s_cselect_b32 s25, s31, s43
	s_cselect_b32 s60, s30, s42
	s_add_u32 s36, s36, 0x40080
	s_addc_u32 s37, s37, 0
	s_add_u32 s61, s42, 0x100
	s_addc_u32 s62, s43, 0
	s_mov_b32 s63, -2
	s_add_u32 s42, s36, 0xfffc0080
	s_addc_u32 s43, s37, -1
	s_add_i32 s64, 0, 0x10000
	s_cmp_eq_u32 s63, 12
	s_cselect_b32 s47, s27, s43
	s_cselect_b32 s46, s59, s42
	v_add_u32_e32 v145, s64, v142
	s_cselect_b32 s43, s25, s62
	s_cselect_b32 s42, s60, s61
	s_add_i32 s66, 0, 0x14000
	ds_read_b128 v[146:149], v145
	ds_read_b128 v[150:153], v145 offset:1024
	ds_read_b128 v[154:157], v145 offset:2048
	ds_read_b128 v[158:161], v145 offset:3072
	v_add_u32_e32 v145, s66, v142
	ds_read_b128 v[162:165], v145
	ds_read_b128 v[166:169], v145 offset:1024
	ds_read_b128 v[170:173], v145 offset:2048
	ds_read_b128 v[174:177], v145 offset:3072
	v_lshl_add_u64 v[220:221], s[36:37], 0, v[138:139]
	s_add_i32 m0, s51, 0xc000
	ds_read_b128 v[178:181], v144
	ds_read_b128 v[182:185], v144 offset:1024
	ds_read_b128 v[186:189], v144 offset:2048
	ds_read_b128 v[190:193], v144 offset:3072
	ds_read_b128 v[204:207], v144 offset:4096
	ds_read_b128 v[208:211], v144 offset:5120
	ds_read_b128 v[212:215], v144 offset:6144
	ds_read_b128 v[216:219], v144 offset:7168
	global_load_lds_dwordx4 v[220:221], off
	v_lshl_add_u64 v[220:221], s[36:37], 0, v[140:141]
	s_add_i32 m0, s51, 0xe000
	s_nop 0
	global_load_lds_dwordx4 v[220:221], off
	s_waitcnt vmcnt(8)
	s_waitcnt lgkmcnt(0)
	s_barrier
	s_setprio 1
	s_waitcnt lgkmcnt(0)
	v_mfma_f32_16x16x32_bf16 v[126:129], v[146:149], v[178:181], 0
	v_mfma_f32_16x16x32_bf16 v[122:125], v[154:157], v[178:181], 0
	v_mfma_f32_16x16x32_bf16 v[110:113], v[146:149], v[186:189], 0
	v_mfma_f32_16x16x32_bf16 v[106:109], v[154:157], v[186:189], 0
	v_mfma_f32_16x16x32_bf16 v[94:97], v[146:149], v[204:207], 0
	v_mfma_f32_16x16x32_bf16 v[90:93], v[154:157], v[204:207], 0
	v_mfma_f32_16x16x32_bf16 v[78:81], v[146:149], v[212:215], 0
	v_mfma_f32_16x16x32_bf16 v[74:77], v[154:157], v[212:215], 0
	v_mfma_f32_16x16x32_bf16 v[126:129], v[150:153], v[182:185], v[126:129]
	v_mfma_f32_16x16x32_bf16 v[122:125], v[158:161], v[182:185], v[122:125]
	v_mfma_f32_16x16x32_bf16 v[110:113], v[150:153], v[190:193], v[110:113]
	v_mfma_f32_16x16x32_bf16 v[106:109], v[158:161], v[190:193], v[106:109]
	v_mfma_f32_16x16x32_bf16 v[94:97], v[150:153], v[208:211], v[94:97]
	v_mfma_f32_16x16x32_bf16 v[90:93], v[158:161], v[208:211], v[90:93]
	v_mfma_f32_16x16x32_bf16 v[78:81], v[150:153], v[216:219], v[78:81]
	v_mfma_f32_16x16x32_bf16 v[74:77], v[158:161], v[216:219], v[74:77]
	s_setprio 0
	s_setprio 1
	v_mfma_f32_16x16x32_bf16 v[118:121], v[162:165], v[178:181], 0
	v_mfma_f32_16x16x32_bf16 v[114:117], v[170:173], v[178:181], 0
	v_mfma_f32_16x16x32_bf16 v[102:105], v[162:165], v[186:189], 0
	v_mfma_f32_16x16x32_bf16 v[98:101], v[170:173], v[186:189], 0
	v_mfma_f32_16x16x32_bf16 v[86:89], v[162:165], v[204:207], 0
	v_mfma_f32_16x16x32_bf16 v[82:85], v[170:173], v[204:207], 0
	v_mfma_f32_16x16x32_bf16 v[70:73], v[162:165], v[212:215], 0
	v_mfma_f32_16x16x32_bf16 v[66:69], v[170:173], v[212:215], 0
	v_mfma_f32_16x16x32_bf16 v[118:121], v[166:169], v[182:185], v[118:121]
	v_mfma_f32_16x16x32_bf16 v[114:117], v[174:177], v[182:185], v[114:117]
	v_mfma_f32_16x16x32_bf16 v[102:105], v[166:169], v[190:193], v[102:105]
	v_mfma_f32_16x16x32_bf16 v[98:101], v[174:177], v[190:193], v[98:101]
	v_mfma_f32_16x16x32_bf16 v[86:89], v[166:169], v[208:211], v[86:89]
	v_mfma_f32_16x16x32_bf16 v[82:85], v[174:177], v[208:211], v[82:85]
	v_mfma_f32_16x16x32_bf16 v[70:73], v[166:169], v[216:219], v[70:73]
	v_mfma_f32_16x16x32_bf16 v[66:69], v[174:177], v[216:219], v[66:69]
	s_setprio 0
	s_barrier
	s_add_i32 s64, s64, s49
	v_lshl_add_u64 v[220:221], s[42:43], 0, v[134:135]
	s_mov_b32 m0, s64
	ds_read_b128 v[178:181], v144 offset:16384
	ds_read_b128 v[182:185], v144 offset:17408
	ds_read_b128 v[186:189], v144 offset:18432
	ds_read_b128 v[190:193], v144 offset:19456
	ds_read_b128 v[204:207], v144 offset:20480
	ds_read_b128 v[208:211], v144 offset:21504
	ds_read_b128 v[212:215], v144 offset:22528
	ds_read_b128 v[216:219], v144 offset:23552
	global_load_lds_dwordx4 v[220:221], off
	s_add_i32 m0, s64, 0x2000
	s_add_u32 s64, s42, 0x40000
	v_lshl_add_u64 v[222:223], s[42:43], 0, v[130:131]
	s_addc_u32 s65, s43, 0
	s_add_i32 s66, s66, s49
	global_load_lds_dwordx4 v[222:223], off
	v_lshl_add_u64 v[224:225], s[64:65], 0, v[134:135]
	s_mov_b32 m0, s66
	v_lshl_add_u64 v[226:227], s[46:47], 0, v[132:133]
	global_load_lds_dwordx4 v[224:225], off
	v_lshl_add_u64 v[224:225], s[64:65], 0, v[130:131]
	s_add_i32 m0, s66, 0x2000
	s_nop 0
	global_load_lds_dwordx4 v[224:225], off
	v_lshl_add_u64 v[224:225], s[46:47], 0, v[136:137]
	s_mov_b32 m0, s51
	s_nop 0
	global_load_lds_dwordx4 v[224:225], off
	s_mov_b32 m0, s52
	s_nop 0
	global_load_lds_dwordx4 v[226:227], off
	s_waitcnt vmcnt(8)
	s_waitcnt lgkmcnt(0)
	s_barrier
; #define PG8_STAGE(bufoff, gbase, voff) do { _Pragma("unroll") for (int _i = 0; _i < 2; ++_i) \
;         __builtin_amdgcn_global_load_lds((const unsigned*)((const char*)(gbase) + (voff)[_i]), (PG8_LAS unsigned*)(lds + (bufoff) + ldsw + _i * 8192), 16, 0, 0); } while (0)
; #define PG8_LDA(dst, b, h) do { _Pragma("unroll") for (int m = 0; m < 4; ++m) _Pragma("unroll") for (int k = 0; k < 2; ++k) dst[m][k] = *(const PG8_LAS bf16x8*)(lds + PG8_SA(b, h) + aoff + m * 2048 + k * 1024); } while (0)
; #define PG8_LDB(dst, b, h) do { _Pragma("unroll") for (int n = 0; n < 2; ++n) _Pragma("unroll") for (int k = 0; k < 2; ++k) dst[n][k] = *(const PG8_LAS bf16x8*)(lds + PG8_SB(b, h) + boff + n * 2048 + k * 1024); } while (0)
; #define PG8_MMA(ai, bj, At, Bt) do { __builtin_amdgcn_s_setprio(1); _Pragma("unroll") for (int m = 0; m < 4; ++m) _Pragma("unroll") for (int n = 0; n < 2; ++n) _Pragma("unroll") for (int k = 0; k < 2; ++k) \
;         acc[ai][bj][m][n] = __builtin_amdgcn_mfma_f32_16x16x32_bf16(Bt[n][k], At[m][k], acc[ai][bj][m][n], 0, 0, 0); __builtin_amdgcn_s_setprio(0); } while (0)
; #define PG8_WAIT_V(n) asm volatile("s_waitcnt vmcnt(" #n ")" ::: "memory")
; #define PG8_WAIT_L(n) asm volatile("s_waitcnt lgkmcnt(" #n ")" ::: "memory")
; #define PG8_BAR __builtin_amdgcn_s_barrier()
; #define PG8_SCHED __builtin_amdgcn_sched_barrier(0)
; template <class Epi, class Sched, bool ALIGN_EPI = false, bool SP2 = false>
; __device__ __forceinline__ void gemm_phase(PG8_LAS unsigned char* lds, const Gemm g, const Sched& S, const Epi& E) {
;     ...
;             PG8_WAIT_V(8); PG8_WAIT_L(0); PG8_BAR; PG8_MMA(0, 0, At, B0); PG8_MMA(0, 1, At, B1); PG8_BAR; PG8_SCHED;
;             PG8_LDA(At, 0, 1); PG8_STAGE(PG8_SB(0, 0), b2, voffB); PG8_STAGE(PG8_SB(0, 1), b2 + hstep, voffB); PG8_STAGE(PG8_SA(0, 0), a2, voffA);
;             PG8_WAIT_V(8); PG8_WAIT_L(0); PG8_BAR; PG8_MMA(1, 0, At, B0); PG8_MMA(1, 1, At, B1); PG8_BAR; PG8_SCHED;
;             PG8_LDB(B0, 1, 0); PG8_LDB(B1, 1, 1); PG8_SCHED; PG8_LDA(At, 1, 0); PG8_STAGE(PG8_SA(0, 1), a2 + hstep, voffA);
;             PG8_WAIT_V(8); PG8_WAIT_L(0); PG8_BAR; PG8_MMA(0, 0, At, B0); PG8_MMA(0, 1, At, B1); PG8_BAR; PG8_SCHED;
	s_setprio 1
	s_waitcnt lgkmcnt(0)
	v_mfma_f32_16x16x32_bf16 v[62:65], v[146:149], v[178:181], 0
	v_mfma_f32_16x16x32_bf16 v[58:61], v[154:157], v[178:181], 0
	v_mfma_f32_16x16x32_bf16 v[46:49], v[146:149], v[186:189], 0
	v_mfma_f32_16x16x32_bf16 v[42:45], v[154:157], v[186:189], 0
	v_mfma_f32_16x16x32_bf16 v[28:31], v[146:149], v[204:207], 0
	v_mfma_f32_16x16x32_bf16 v[24:27], v[154:157], v[204:207], 0
	v_mfma_f32_16x16x32_bf16 v[12:15], v[146:149], v[212:215], 0
	v_mfma_f32_16x16x32_bf16 v[8:11], v[154:157], v[212:215], 0
	v_mfma_f32_16x16x32_bf16 v[62:65], v[150:153], v[182:185], v[62:65]
	v_mfma_f32_16x16x32_bf16 v[58:61], v[158:161], v[182:185], v[58:61]
	v_mfma_f32_16x16x32_bf16 v[46:49], v[150:153], v[190:193], v[46:49]
	v_mfma_f32_16x16x32_bf16 v[42:45], v[158:161], v[190:193], v[42:45]
	v_mfma_f32_16x16x32_bf16 v[28:31], v[150:153], v[208:211], v[28:31]
	v_mfma_f32_16x16x32_bf16 v[24:27], v[158:161], v[208:211], v[24:27]
	v_mfma_f32_16x16x32_bf16 v[12:15], v[150:153], v[216:219], v[12:15]
	v_mfma_f32_16x16x32_bf16 v[8:11], v[158:161], v[216:219], v[8:11]
	s_setprio 0
	s_setprio 1
	v_mfma_f32_16x16x32_bf16 v[54:57], v[162:165], v[178:181], 0
	v_mfma_f32_16x16x32_bf16 v[50:53], v[170:173], v[178:181], 0
	v_mfma_f32_16x16x32_bf16 v[38:41], v[162:165], v[186:189], 0
	v_mfma_f32_16x16x32_bf16 v[34:37], v[170:173], v[186:189], 0
	v_mfma_f32_16x16x32_bf16 v[20:23], v[162:165], v[204:207], 0
	v_mfma_f32_16x16x32_bf16 v[16:19], v[170:173], v[204:207], 0
	v_mfma_f32_16x16x32_bf16 v[4:7], v[162:165], v[212:215], 0
	v_mfma_f32_16x16x32_bf16 v[0:3], v[170:173], v[212:215], 0
	v_mfma_f32_16x16x32_bf16 v[54:57], v[166:169], v[182:185], v[54:57]
	v_mfma_f32_16x16x32_bf16 v[50:53], v[174:177], v[182:185], v[50:53]
	v_mfma_f32_16x16x32_bf16 v[38:41], v[166:169], v[190:193], v[38:41]
	v_mfma_f32_16x16x32_bf16 v[34:37], v[174:177], v[190:193], v[34:37]
	v_mfma_f32_16x16x32_bf16 v[20:23], v[166:169], v[208:211], v[20:23]
	v_mfma_f32_16x16x32_bf16 v[16:19], v[174:177], v[208:211], v[16:19]
	v_mfma_f32_16x16x32_bf16 v[4:7], v[166:169], v[216:219], v[4:7]
	v_mfma_f32_16x16x32_bf16 v[0:3], v[174:177], v[216:219], v[0:3]
	s_setprio 0
	s_barrier
	s_add_i32 s64, 0, 0x18000
	v_add_u32_e32 v145, s64, v142
	s_add_i32 s65, 0, 0x1c000
	ds_read_b128 v[146:149], v145
	ds_read_b128 v[150:153], v145 offset:1024
	ds_read_b128 v[154:157], v145 offset:2048
	ds_read_b128 v[158:161], v145 offset:3072
	v_add_u32_e32 v145, s65, v142
	ds_read_b128 v[162:165], v145
	ds_read_b128 v[166:169], v145 offset:1024
	ds_read_b128 v[170:173], v145 offset:2048
	ds_read_b128 v[174:177], v145 offset:3072
	s_add_u32 s46, s46, 0x40000
	s_addc_u32 s47, s47, 0
	s_mov_b32 m0, s53
	v_lshl_add_u64 v[238:239], s[46:47], 0, v[136:137]
	ds_read_b128 v[178:181], v144 offset:32768
	ds_read_b128 v[182:185], v144 offset:33792
	ds_read_b128 v[186:189], v144 offset:34816
	ds_read_b128 v[190:193], v144 offset:35840
	ds_read_b128 v[204:207], v144 offset:36864
	ds_read_b128 v[208:211], v144 offset:37888
	ds_read_b128 v[212:215], v144 offset:38912
	ds_read_b128 v[216:219], v144 offset:39936
	global_load_lds_dwordx4 v[238:239], off
	v_lshl_add_u64 v[238:239], s[46:47], 0, v[132:133]
	s_mov_b32 m0, s55
	s_nop 0
	global_load_lds_dwordx4 v[238:239], off
	s_waitcnt vmcnt(8)
	s_waitcnt lgkmcnt(0)
	s_barrier
	s_setprio 1
	s_waitcnt lgkmcnt(0)
	v_mfma_f32_16x16x32_bf16 v[126:129], v[146:149], v[178:181], v[126:129]
	v_mfma_f32_16x16x32_bf16 v[122:125], v[154:157], v[178:181], v[122:125]
	v_mfma_f32_16x16x32_bf16 v[110:113], v[146:149], v[186:189], v[110:113]
	v_mfma_f32_16x16x32_bf16 v[106:109], v[154:157], v[186:189], v[106:109]
	v_mfma_f32_16x16x32_bf16 v[94:97], v[146:149], v[204:207], v[94:97]
	v_mfma_f32_16x16x32_bf16 v[90:93], v[154:157], v[204:207], v[90:93]
	v_mfma_f32_16x16x32_bf16 v[78:81], v[146:149], v[212:215], v[78:81]
	v_mfma_f32_16x16x32_bf16 v[74:77], v[154:157], v[212:215], v[74:77]
	v_mfma_f32_16x16x32_bf16 v[126:129], v[150:153], v[182:185], v[126:129]
	v_mfma_f32_16x16x32_bf16 v[122:125], v[158:161], v[182:185], v[122:125]
	v_mfma_f32_16x16x32_bf16 v[110:113], v[150:153], v[190:193], v[110:113]
	v_mfma_f32_16x16x32_bf16 v[106:109], v[158:161], v[190:193], v[106:109]
	v_mfma_f32_16x16x32_bf16 v[94:97], v[150:153], v[208:211], v[94:97]
	v_mfma_f32_16x16x32_bf16 v[90:93], v[158:161], v[208:211], v[90:93]
	v_mfma_f32_16x16x32_bf16 v[78:81], v[150:153], v[216:219], v[78:81]
	v_mfma_f32_16x16x32_bf16 v[74:77], v[158:161], v[216:219], v[74:77]
	s_setprio 0
	s_setprio 1
	v_mfma_f32_16x16x32_bf16 v[118:121], v[162:165], v[178:181], v[118:121]
	v_mfma_f32_16x16x32_bf16 v[114:117], v[170:173], v[178:181], v[114:117]
	v_mfma_f32_16x16x32_bf16 v[102:105], v[162:165], v[186:189], v[102:105]
	v_mfma_f32_16x16x32_bf16 v[98:101], v[170:173], v[186:189], v[98:101]
	v_mfma_f32_16x16x32_bf16 v[86:89], v[162:165], v[204:207], v[86:89]
	v_mfma_f32_16x16x32_bf16 v[82:85], v[170:173], v[204:207], v[82:85]
	v_mfma_f32_16x16x32_bf16 v[70:73], v[162:165], v[212:215], v[70:73]
	v_mfma_f32_16x16x32_bf16 v[66:69], v[170:173], v[212:215], v[66:69]
	v_mfma_f32_16x16x32_bf16 v[118:121], v[166:169], v[182:185], v[118:121]
	v_mfma_f32_16x16x32_bf16 v[114:117], v[174:177], v[182:185], v[114:117]
	v_mfma_f32_16x16x32_bf16 v[102:105], v[166:169], v[190:193], v[102:105]
	v_mfma_f32_16x16x32_bf16 v[98:101], v[174:177], v[190:193], v[98:101]
	v_mfma_f32_16x16x32_bf16 v[86:89], v[166:169], v[208:211], v[86:89]
	v_mfma_f32_16x16x32_bf16 v[82:85], v[174:177], v[208:211], v[82:85]
	v_mfma_f32_16x16x32_bf16 v[70:73], v[166:169], v[216:219], v[70:73]
	v_mfma_f32_16x16x32_bf16 v[66:69], v[174:177], v[216:219], v[66:69]
	s_setprio 0
	s_barrier
; #define PG8_STAGE(bufoff, gbase, voff) do { _Pragma("unroll") for (int _i = 0; _i < 2; ++_i) \
;         __builtin_amdgcn_global_load_lds((const unsigned*)((const char*)(gbase) + (voff)[_i]), (PG8_LAS unsigned*)(lds + (bufoff) + ldsw + _i * 8192), 16, 0, 0); } while (0)
; #define PG8_LDA(dst, b, h) do { _Pragma("unroll") for (int m = 0; m < 4; ++m) _Pragma("unroll") for (int k = 0; k < 2; ++k) dst[m][k] = *(const PG8_LAS bf16x8*)(lds + PG8_SA(b, h) + aoff + m * 2048 + k * 1024); } while (0)
; #define PG8_LDB(dst, b, h) do { _Pragma("unroll") for (int n = 0; n < 2; ++n) _Pragma("unroll") for (int k = 0; k < 2; ++k) dst[n][k] = *(const PG8_LAS bf16x8*)(lds + PG8_SB(b, h) + boff + n * 2048 + k * 1024); } while (0)
; #define PG8_MMA(ai, bj, At, Bt) do { __builtin_amdgcn_s_setprio(1); _Pragma("unroll") for (int m = 0; m < 4; ++m) _Pragma("unroll") for (int n = 0; n < 2; ++n) _Pragma("unroll") for (int k = 0; k < 2; ++k) \
;         acc[ai][bj][m][n] = __builtin_amdgcn_mfma_f32_16x16x32_bf16(Bt[n][k], At[m][k], acc[ai][bj][m][n], 0, 0, 0); __builtin_amdgcn_s_setprio(0); } while (0)
; template <class Epi, class Sched, bool ALIGN_EPI = false, bool SP2 = false>
; __device__ __forceinline__ void gemm_phase(PG8_LAS unsigned char* lds, const Gemm g, const Sched& S, const Epi& E) {
;     ...
;         for (int t = 0; t < nt; t += 2) {
;             const bool last = (t == nt - 2);
;             const char* a1 = cA + (size_t)(t + 1) * kstep;
;             const char* a2 = last ? nA : cA + (size_t)(t + 2) * kstep; const char* b2 = last ? nB : cB + (size_t)(t + 2) * kstep;
;             const char* a3 = a2 + kstep; const char* b3 = b2 + kstep;
;             if (last && has_next) S.a_ready(nxt);
;             if constexpr (SP2) {
;             PG8_LDB(B0, 0, 0); PG8_LDB(B1, 0, 1); PG8_SCHED; PG8_LDA(At, 0, 0); PG8_STAGE(PG8_SA(1, 1), a1 + hstep, voffA);
;             PG8_WAIT_V(8); PG8_WAIT_L(0); PG8_BAR; PG8_MMA(0, 0, At, B0); PG8_MMA(0, 1, At, B1); PG8_BAR; PG8_SCHED;
;     ...
;             PG8_WAIT_V(8); PG8_WAIT_L(0); PG8_BAR; PG8_MMA(0, 0, At, B0); PG8_MMA(0, 1, At, B1); PG8_BAR; PG8_SCHED;
;             PG8_LDA(At, 1, 1); PG8_STAGE(PG8_SB(1, 0), b3, voffB); PG8_STAGE(PG8_SB(1, 1), b3 + hstep, voffB); PG8_STAGE(PG8_SA(1, 0), a3, voffA);
;             PG8_WAIT_V(8); PG8_WAIT_L(0); PG8_BAR; PG8_MMA(1, 0, At, B0); PG8_MMA(1, 1, At, B1); PG8_BAR; PG8_SCHED;
	s_add_i32 s46, s64, s49
	v_lshl_add_u64 v[220:221], v[220:221], 0, s[8:9]
	s_mov_b32 m0, s46
	ds_read_b128 v[178:181], v144 offset:49152
	ds_read_b128 v[182:185], v144 offset:50176
	ds_read_b128 v[186:189], v144 offset:51200
	ds_read_b128 v[190:193], v144 offset:52224
	ds_read_b128 v[204:207], v144 offset:53248
	ds_read_b128 v[208:211], v144 offset:54272
	ds_read_b128 v[212:215], v144 offset:55296
	ds_read_b128 v[216:219], v144 offset:56320
	global_load_lds_dwordx4 v[220:221], off
	s_add_i32 m0, s46, 0x2000
	s_add_u32 s42, s42, 0x40080
	v_lshl_add_u64 v[220:221], v[222:223], 0, s[8:9]
	s_addc_u32 s43, s43, 0
	s_add_i32 s46, s65, s49
	global_load_lds_dwordx4 v[220:221], off
	v_lshl_add_u64 v[220:221], s[42:43], 0, v[134:135]
	s_mov_b32 m0, s46
	s_nop 0
	global_load_lds_dwordx4 v[220:221], off
	v_lshl_add_u64 v[220:221], s[42:43], 0, v[130:131]
	s_add_i32 m0, s46, 0x2000
	s_nop 0
	global_load_lds_dwordx4 v[220:221], off
	v_lshl_add_u64 v[220:221], v[224:225], 0, s[8:9]
	s_mov_b32 m0, s56
	s_nop 0
	global_load_lds_dwordx4 v[220:221], off
	v_lshl_add_u64 v[220:221], v[226:227], 0, s[8:9]
	s_mov_b32 m0, s57
	s_nop 0
	global_load_lds_dwordx4 v[220:221], off
	s_waitcnt vmcnt(8)
	s_waitcnt lgkmcnt(0)
	s_barrier
	s_setprio 1
	s_waitcnt lgkmcnt(0)
	v_mfma_f32_16x16x32_bf16 v[62:65], v[146:149], v[178:181], v[62:65]
	v_mfma_f32_16x16x32_bf16 v[58:61], v[154:157], v[178:181], v[58:61]
	v_mfma_f32_16x16x32_bf16 v[46:49], v[146:149], v[186:189], v[46:49]
	v_mfma_f32_16x16x32_bf16 v[42:45], v[154:157], v[186:189], v[42:45]
	v_mfma_f32_16x16x32_bf16 v[28:31], v[146:149], v[204:207], v[28:31]
	v_mfma_f32_16x16x32_bf16 v[24:27], v[154:157], v[204:207], v[24:27]
	v_mfma_f32_16x16x32_bf16 v[12:15], v[146:149], v[212:215], v[12:15]
	v_mfma_f32_16x16x32_bf16 v[8:11], v[154:157], v[212:215], v[8:11]
	v_mfma_f32_16x16x32_bf16 v[62:65], v[150:153], v[182:185], v[62:65]
	v_mfma_f32_16x16x32_bf16 v[58:61], v[158:161], v[182:185], v[58:61]
	v_mfma_f32_16x16x32_bf16 v[46:49], v[150:153], v[190:193], v[46:49]
	v_mfma_f32_16x16x32_bf16 v[42:45], v[158:161], v[190:193], v[42:45]
	v_mfma_f32_16x16x32_bf16 v[28:31], v[150:153], v[208:211], v[28:31]
	v_mfma_f32_16x16x32_bf16 v[24:27], v[158:161], v[208:211], v[24:27]
	v_mfma_f32_16x16x32_bf16 v[12:15], v[150:153], v[216:219], v[12:15]
	v_mfma_f32_16x16x32_bf16 v[8:11], v[158:161], v[216:219], v[8:11]
	s_setprio 0
	s_setprio 1
	v_mfma_f32_16x16x32_bf16 v[54:57], v[162:165], v[178:181], v[54:57]
	v_mfma_f32_16x16x32_bf16 v[50:53], v[170:173], v[178:181], v[50:53]
	v_mfma_f32_16x16x32_bf16 v[38:41], v[162:165], v[186:189], v[38:41]
	v_mfma_f32_16x16x32_bf16 v[34:37], v[170:173], v[186:189], v[34:37]
	v_mfma_f32_16x16x32_bf16 v[20:23], v[162:165], v[204:207], v[20:23]
	v_mfma_f32_16x16x32_bf16 v[16:19], v[170:173], v[204:207], v[16:19]
	v_mfma_f32_16x16x32_bf16 v[4:7], v[162:165], v[212:215], v[4:7]
	v_mfma_f32_16x16x32_bf16 v[0:3], v[170:173], v[212:215], v[0:3]
	v_mfma_f32_16x16x32_bf16 v[54:57], v[166:169], v[182:185], v[54:57]
	v_mfma_f32_16x16x32_bf16 v[50:53], v[174:177], v[182:185], v[50:53]
	v_mfma_f32_16x16x32_bf16 v[38:41], v[166:169], v[190:193], v[38:41]
	v_mfma_f32_16x16x32_bf16 v[34:37], v[174:177], v[190:193], v[34:37]
	v_mfma_f32_16x16x32_bf16 v[20:23], v[166:169], v[208:211], v[20:23]
	v_mfma_f32_16x16x32_bf16 v[16:19], v[174:177], v[208:211], v[16:19]
	v_mfma_f32_16x16x32_bf16 v[4:7], v[166:169], v[216:219], v[4:7]
	v_mfma_f32_16x16x32_bf16 v[0:3], v[174:177], v[216:219], v[0:3]
	s_setprio 0
	s_barrier
	s_add_i32 s63, s63, 2
	s_add_u32 s36, s36, 0x100
	s_addc_u32 s37, s37, 0
	s_add_u32 s61, s61, 0x100
	s_addc_u32 s62, s62, 0
	s_cmp_gt_u32 s63, 13
	s_cbranch_scc1 .Lgx3
.LBB0_936:
	s_add_u32 s42, s36, 0xfffc0080
	s_addc_u32 s43, s37, -1
	s_add_i32 s64, 0, 0x10000
	s_cmp_eq_u32 s63, 12
	s_cselect_b32 s47, s27, s43
	s_cselect_b32 s46, s59, s42
	v_add_u32_e32 v145, s64, v142
	s_cselect_b32 s43, s25, s62
	s_cselect_b32 s42, s60, s61
	s_add_i32 s66, 0, 0x14000
	ds_read_b128 v[146:149], v145
	ds_read_b128 v[150:153], v145 offset:1024
	ds_read_b128 v[154:157], v145 offset:2048
	ds_read_b128 v[158:161], v145 offset:3072
	v_add_u32_e32 v145, s66, v142
	ds_read_b128 v[162:165], v145
	ds_read_b128 v[166:169], v145 offset:1024
	ds_read_b128 v[170:173], v145 offset:2048
	ds_read_b128 v[174:177], v145 offset:3072
	v_lshl_add_u64 v[220:221], s[36:37], 0, v[138:139]
	s_add_i32 m0, s51, 0xc000
	ds_read_b128 v[178:181], v144
	ds_read_b128 v[182:185], v144 offset:1024
	ds_read_b128 v[186:189], v144 offset:2048
	ds_read_b128 v[190:193], v144 offset:3072
	ds_read_b128 v[204:207], v144 offset:4096
	ds_read_b128 v[208:211], v144 offset:5120
	ds_read_b128 v[212:215], v144 offset:6144
	ds_read_b128 v[216:219], v144 offset:7168
	global_load_lds_dwordx4 v[220:221], off
	v_lshl_add_u64 v[220:221], s[36:37], 0, v[140:141]
	s_add_i32 m0, s51, 0xe000
	s_nop 0
	global_load_lds_dwordx4 v[220:221], off
	s_waitcnt vmcnt(8)
	s_waitcnt lgkmcnt(0)
	s_barrier
; #define PG8_STAGE(bufoff, gbase, voff) do { _Pragma("unroll") for (int _i = 0; _i < 2; ++_i) \
;         __builtin_amdgcn_global_load_lds((const unsigned*)((const char*)(gbase) + (voff)[_i]), (PG8_LAS unsigned*)(lds + (bufoff) + ldsw + _i * 8192), 16, 0, 0); } while (0)
; #define PG8_LDA(dst, b, h) do { _Pragma("unroll") for (int m = 0; m < 4; ++m) _Pragma("unroll") for (int k = 0; k < 2; ++k) dst[m][k] = *(const PG8_LAS bf16x8*)(lds + PG8_SA(b, h) + aoff + m * 2048 + k * 1024); } while (0)
; #define PG8_LDB(dst, b, h) do { _Pragma("unroll") for (int n = 0; n < 2; ++n) _Pragma("unroll") for (int k = 0; k < 2; ++k) dst[n][k] = *(const PG8_LAS bf16x8*)(lds + PG8_SB(b, h) + boff + n * 2048 + k * 1024); } while (0)
; #define PG8_MMA(ai, bj, At, Bt) do { __builtin_amdgcn_s_setprio(1); _Pragma("unroll") for (int m = 0; m < 4; ++m) _Pragma("unroll") for (int n = 0; n < 2; ++n) _Pragma("unroll") for (int k = 0; k < 2; ++k) \
;         acc[ai][bj][m][n] = __builtin_amdgcn_mfma_f32_16x16x32_bf16(Bt[n][k], At[m][k], acc[ai][bj][m][n], 0, 0, 0); __builtin_amdgcn_s_setprio(0); } while (0)
; #define PG8_WAIT_V(n) asm volatile("s_waitcnt vmcnt(" #n ")" ::: "memory")
; #define PG8_WAIT_L(n) asm volatile("s_waitcnt lgkmcnt(" #n ")" ::: "memory")
; #define PG8_BAR __builtin_amdgcn_s_barrier()
; #define PG8_SCHED __builtin_amdgcn_sched_barrier(0)
; template <class Epi, class Sched, bool ALIGN_EPI = false, bool SP2 = false>
; __device__ __forceinline__ void gemm_phase(PG8_LAS unsigned char* lds, const Gemm g, const Sched& S, const Epi& E) {
;     ...
;             PG8_WAIT_V(8); PG8_WAIT_L(0); PG8_BAR; PG8_MMA(0, 0, At, B0); PG8_MMA(0, 1, At, B1); PG8_BAR; PG8_SCHED;
;             PG8_LDA(At, 0, 1); PG8_STAGE(PG8_SB(0, 0), b2, voffB); PG8_STAGE(PG8_SB(0, 1), b2 + hstep, voffB); PG8_STAGE(PG8_SA(0, 0), a2, voffA);
;             PG8_WAIT_V(8); PG8_WAIT_L(0); PG8_BAR; PG8_MMA(1, 0, At, B0); PG8_MMA(1, 1, At, B1); PG8_BAR; PG8_SCHED;
;             PG8_LDB(B0, 1, 0); PG8_LDB(B1, 1, 1); PG8_SCHED; PG8_LDA(At, 1, 0); PG8_STAGE(PG8_SA(0, 1), a2 + hstep, voffA);
;             PG8_WAIT_V(8); PG8_WAIT_L(0); PG8_BAR; PG8_MMA(0, 0, At, B0); PG8_MMA(0, 1, At, B1); PG8_BAR; PG8_SCHED;
	s_setprio 1
	s_waitcnt lgkmcnt(0)
	v_mfma_f32_16x16x32_bf16 v[126:129], v[146:149], v[178:181], v[126:129]
	v_mfma_f32_16x16x32_bf16 v[122:125], v[154:157], v[178:181], v[122:125]
	v_mfma_f32_16x16x32_bf16 v[110:113], v[146:149], v[186:189], v[110:113]
	v_mfma_f32_16x16x32_bf16 v[106:109], v[154:157], v[186:189], v[106:109]
	v_mfma_f32_16x16x32_bf16 v[94:97], v[146:149], v[204:207], v[94:97]
	v_mfma_f32_16x16x32_bf16 v[90:93], v[154:157], v[204:207], v[90:93]
	v_mfma_f32_16x16x32_bf16 v[78:81], v[146:149], v[212:215], v[78:81]
	v_mfma_f32_16x16x32_bf16 v[74:77], v[154:157], v[212:215], v[74:77]
	v_mfma_f32_16x16x32_bf16 v[126:129], v[150:153], v[182:185], v[126:129]
	v_mfma_f32_16x16x32_bf16 v[122:125], v[158:161], v[182:185], v[122:125]
	v_mfma_f32_16x16x32_bf16 v[110:113], v[150:153], v[190:193], v[110:113]
	v_mfma_f32_16x16x32_bf16 v[106:109], v[158:161], v[190:193], v[106:109]
	v_mfma_f32_16x16x32_bf16 v[94:97], v[150:153], v[208:211], v[94:97]
	v_mfma_f32_16x16x32_bf16 v[90:93], v[158:161], v[208:211], v[90:93]
	v_mfma_f32_16x16x32_bf16 v[78:81], v[150:153], v[216:219], v[78:81]
	v_mfma_f32_16x16x32_bf16 v[74:77], v[158:161], v[216:219], v[74:77]
	s_setprio 0
	s_setprio 1
	v_mfma_f32_16x16x32_bf16 v[118:121], v[162:165], v[178:181], v[118:121]
	v_mfma_f32_16x16x32_bf16 v[114:117], v[170:173], v[178:181], v[114:117]
	v_mfma_f32_16x16x32_bf16 v[102:105], v[162:165], v[186:189], v[102:105]
	v_mfma_f32_16x16x32_bf16 v[98:101], v[170:173], v[186:189], v[98:101]
	v_mfma_f32_16x16x32_bf16 v[86:89], v[162:165], v[204:207], v[86:89]
	v_mfma_f32_16x16x32_bf16 v[82:85], v[170:173], v[204:207], v[82:85]
	v_mfma_f32_16x16x32_bf16 v[70:73], v[162:165], v[212:215], v[70:73]
	v_mfma_f32_16x16x32_bf16 v[66:69], v[170:173], v[212:215], v[66:69]
	v_mfma_f32_16x16x32_bf16 v[118:121], v[166:169], v[182:185], v[118:121]
	v_mfma_f32_16x16x32_bf16 v[114:117], v[174:177], v[182:185], v[114:117]
	v_mfma_f32_16x16x32_bf16 v[102:105], v[166:169], v[190:193], v[102:105]
	v_mfma_f32_16x16x32_bf16 v[98:101], v[174:177], v[190:193], v[98:101]
	v_mfma_f32_16x16x32_bf16 v[86:89], v[166:169], v[208:211], v[86:89]
	v_mfma_f32_16x16x32_bf16 v[82:85], v[174:177], v[208:211], v[82:85]
	v_mfma_f32_16x16x32_bf16 v[70:73], v[166:169], v[216:219], v[70:73]
	v_mfma_f32_16x16x32_bf16 v[66:69], v[174:177], v[216:219], v[66:69]
	s_setprio 0
	s_barrier
	s_add_i32 s64, s64, s49
	v_lshl_add_u64 v[220:221], s[42:43], 0, v[134:135]
	s_mov_b32 m0, s64
	ds_read_b128 v[178:181], v144 offset:16384
	ds_read_b128 v[182:185], v144 offset:17408
	ds_read_b128 v[186:189], v144 offset:18432
	ds_read_b128 v[190:193], v144 offset:19456
	ds_read_b128 v[204:207], v144 offset:20480
	ds_read_b128 v[208:211], v144 offset:21504
	ds_read_b128 v[212:215], v144 offset:22528
	ds_read_b128 v[216:219], v144 offset:23552
	global_load_lds_dwordx4 v[220:221], off
	s_add_i32 m0, s64, 0x2000
	s_add_u32 s64, s42, 0x40000
	v_lshl_add_u64 v[222:223], s[42:43], 0, v[130:131]
	s_addc_u32 s65, s43, 0
	s_add_i32 s66, s66, s49
	global_load_lds_dwordx4 v[222:223], off
	v_lshl_add_u64 v[224:225], s[64:65], 0, v[134:135]
	s_mov_b32 m0, s66
	v_lshl_add_u64 v[226:227], s[46:47], 0, v[132:133]
	global_load_lds_dwordx4 v[224:225], off
	v_lshl_add_u64 v[224:225], s[64:65], 0, v[130:131]
	s_add_i32 m0, s66, 0x2000
	s_nop 0
	global_load_lds_dwordx4 v[224:225], off
	v_lshl_add_u64 v[224:225], s[46:47], 0, v[136:137]
	s_mov_b32 m0, s51
	s_nop 0
	global_load_lds_dwordx4 v[224:225], off
	s_mov_b32 m0, s52
	s_nop 0
	global_load_lds_dwordx4 v[226:227], off
	s_waitcnt vmcnt(8)
	s_waitcnt lgkmcnt(0)
	s_barrier
	s_setprio 1
	s_waitcnt lgkmcnt(0)
	v_mfma_f32_16x16x32_bf16 v[62:65], v[146:149], v[178:181], v[62:65]
	v_mfma_f32_16x16x32_bf16 v[58:61], v[154:157], v[178:181], v[58:61]
	v_mfma_f32_16x16x32_bf16 v[46:49], v[146:149], v[186:189], v[46:49]
	v_mfma_f32_16x16x32_bf16 v[42:45], v[154:157], v[186:189], v[42:45]
	v_mfma_f32_16x16x32_bf16 v[28:31], v[146:149], v[204:207], v[28:31]
	v_mfma_f32_16x16x32_bf16 v[24:27], v[154:157], v[204:207], v[24:27]
	v_mfma_f32_16x16x32_bf16 v[12:15], v[146:149], v[212:215], v[12:15]
	v_mfma_f32_16x16x32_bf16 v[8:11], v[154:157], v[212:215], v[8:11]
	v_mfma_f32_16x16x32_bf16 v[62:65], v[150:153], v[182:185], v[62:65]
	v_mfma_f32_16x16x32_bf16 v[58:61], v[158:161], v[182:185], v[58:61]
	v_mfma_f32_16x16x32_bf16 v[46:49], v[150:153], v[190:193], v[46:49]
	v_mfma_f32_16x16x32_bf16 v[42:45], v[158:161], v[190:193], v[42:45]
	v_mfma_f32_16x16x32_bf16 v[28:31], v[150:153], v[208:211], v[28:31]
	v_mfma_f32_16x16x32_bf16 v[24:27], v[158:161], v[208:211], v[24:27]
	v_mfma_f32_16x16x32_bf16 v[12:15], v[150:153], v[216:219], v[12:15]
	v_mfma_f32_16x16x32_bf16 v[8:11], v[158:161], v[216:219], v[8:11]
	s_setprio 0
	s_setprio 1
	v_mfma_f32_16x16x32_bf16 v[54:57], v[162:165], v[178:181], v[54:57]
	v_mfma_f32_16x16x32_bf16 v[50:53], v[170:173], v[178:181], v[50:53]
	v_mfma_f32_16x16x32_bf16 v[38:41], v[162:165], v[186:189], v[38:41]
	v_mfma_f32_16x16x32_bf16 v[34:37], v[170:173], v[186:189], v[34:37]
	v_mfma_f32_16x16x32_bf16 v[20:23], v[162:165], v[204:207], v[20:23]
	v_mfma_f32_16x16x32_bf16 v[16:19], v[170:173], v[204:207], v[16:19]
	v_mfma_f32_16x16x32_bf16 v[4:7], v[162:165], v[212:215], v[4:7]
	v_mfma_f32_16x16x32_bf16 v[0:3], v[170:173], v[212:215], v[0:3]
	v_mfma_f32_16x16x32_bf16 v[54:57], v[166:169], v[182:185], v[54:57]
	v_mfma_f32_16x16x32_bf16 v[50:53], v[174:177], v[182:185], v[50:53]
	v_mfma_f32_16x16x32_bf16 v[38:41], v[166:169], v[190:193], v[38:41]
	v_mfma_f32_16x16x32_bf16 v[34:37], v[174:177], v[190:193], v[34:37]
	v_mfma_f32_16x16x32_bf16 v[20:23], v[166:169], v[208:211], v[20:23]
	v_mfma_f32_16x16x32_bf16 v[16:19], v[174:177], v[208:211], v[16:19]
	v_mfma_f32_16x16x32_bf16 v[4:7], v[166:169], v[216:219], v[4:7]
	v_mfma_f32_16x16x32_bf16 v[0:3], v[174:177], v[216:219], v[0:3]
	s_setprio 0
	s_barrier
; #define PG8_STAGE(bufoff, gbase, voff) do { _Pragma("unroll") for (int _i = 0; _i < 2; ++_i) \
;         __builtin_amdgcn_global_load_lds((const unsigned*)((const char*)(gbase) + (voff)[_i]), (PG8_LAS unsigned*)(lds + (bufoff) + ldsw + _i * 8192), 16, 0, 0); } while (0)
; #define PG8_LDA(dst, b, h) do { _Pragma("unroll") for (int m = 0; m < 4; ++m) _Pragma("unroll") for (int k = 0; k < 2; ++k) dst[m][k] = *(const PG8_LAS bf16x8*)(lds + PG8_SA(b, h) + aoff + m * 2048 + k * 1024); } while (0)
; #define PG8_LDB(dst, b, h) do { _Pragma("unroll") for (int n = 0; n < 2; ++n) _Pragma("unroll") for (int k = 0; k < 2; ++k) dst[n][k] = *(const PG8_LAS bf16x8*)(lds + PG8_SB(b, h) + boff + n * 2048 + k * 1024); } while (0)
; #define PG8_MMA(ai, bj, At, Bt) do { __builtin_amdgcn_s_setprio(1); _Pragma("unroll") for (int m = 0; m < 4; ++m) _Pragma("unroll") for (int n = 0; n < 2; ++n) _Pragma("unroll") for (int k = 0; k < 2; ++k) \
;         acc[ai][bj][m][n] = __builtin_amdgcn_mfma_f32_16x16x32_bf16(Bt[n][k], At[m][k], acc[ai][bj][m][n], 0, 0, 0); __builtin_amdgcn_s_setprio(0); } while (0)
; #define PG8_WAIT_V(n) asm volatile("s_waitcnt vmcnt(" #n ")" ::: "memory")
; #define PG8_WAIT_L(n) asm volatile("s_waitcnt lgkmcnt(" #n ")" ::: "memory")
; #define PG8_BAR __builtin_amdgcn_s_barrier()
; #define PG8_SCHED __builtin_amdgcn_sched_barrier(0)
; template <class Epi, class Sched, bool ALIGN_EPI = false, bool SP2 = false>
; __device__ __forceinline__ void gemm_phase(PG8_LAS unsigned char* lds, const Gemm g, const Sched& S, const Epi& E) {
;     ...
;             PG8_LDB(B0, 1, 0); PG8_LDB(B1, 1, 1); PG8_SCHED; PG8_LDA(At, 1, 0); PG8_STAGE(PG8_SA(0, 1), a2 + hstep, voffA);
;             PG8_WAIT_V(8); PG8_WAIT_L(0); PG8_BAR; PG8_MMA(0, 0, At, B0); PG8_MMA(0, 1, At, B1); PG8_BAR; PG8_SCHED;
	s_add_i32 s64, 0, 0x18000
	v_add_u32_e32 v145, s64, v142
	s_add_i32 s65, 0, 0x1c000
	ds_read_b128 v[146:149], v145
	ds_read_b128 v[150:153], v145 offset:1024
	ds_read_b128 v[154:157], v145 offset:2048
	ds_read_b128 v[158:161], v145 offset:3072
	v_add_u32_e32 v145, s65, v142
	ds_read_b128 v[162:165], v145
	ds_read_b128 v[166:169], v145 offset:1024
	ds_read_b128 v[170:173], v145 offset:2048
	ds_read_b128 v[174:177], v145 offset:3072
	s_add_u32 s46, s46, 0x40000
	s_addc_u32 s47, s47, 0
	s_mov_b32 m0, s53
	v_lshl_add_u64 v[238:239], s[46:47], 0, v[136:137]
	ds_read_b128 v[178:181], v144 offset:32768
	ds_read_b128 v[182:185], v144 offset:33792
	ds_read_b128 v[186:189], v144 offset:34816
	ds_read_b128 v[190:193], v144 offset:35840
	ds_read_b128 v[204:207], v144 offset:36864
	ds_read_b128 v[208:211], v144 offset:37888
	ds_read_b128 v[212:215], v144 offset:38912
	ds_read_b128 v[216:219], v144 offset:39936
	global_load_lds_dwordx4 v[238:239], off
	v_lshl_add_u64 v[238:239], s[46:47], 0, v[132:133]
	s_mov_b32 m0, s55
	s_nop 0
	global_load_lds_dwordx4 v[238:239], off
	s_waitcnt vmcnt(8)
	s_waitcnt lgkmcnt(0)
	s_barrier
	s_setprio 1
	s_waitcnt lgkmcnt(0)
	v_mfma_f32_16x16x32_bf16 v[126:129], v[146:149], v[178:181], v[126:129]
	v_mfma_f32_16x16x32_bf16 v[122:125], v[154:157], v[178:181], v[122:125]
	v_mfma_f32_16x16x32_bf16 v[110:113], v[146:149], v[186:189], v[110:113]
	v_mfma_f32_16x16x32_bf16 v[106:109], v[154:157], v[186:189], v[106:109]
	v_mfma_f32_16x16x32_bf16 v[94:97], v[146:149], v[204:207], v[94:97]
	v_mfma_f32_16x16x32_bf16 v[90:93], v[154:157], v[204:207], v[90:93]
	v_mfma_f32_16x16x32_bf16 v[78:81], v[146:149], v[212:215], v[78:81]
	v_mfma_f32_16x16x32_bf16 v[74:77], v[154:157], v[212:215], v[74:77]
	v_mfma_f32_16x16x32_bf16 v[126:129], v[150:153], v[182:185], v[126:129]
	v_mfma_f32_16x16x32_bf16 v[122:125], v[158:161], v[182:185], v[122:125]
	v_mfma_f32_16x16x32_bf16 v[110:113], v[150:153], v[190:193], v[110:113]
	v_mfma_f32_16x16x32_bf16 v[106:109], v[158:161], v[190:193], v[106:109]
	v_mfma_f32_16x16x32_bf16 v[94:97], v[150:153], v[208:211], v[94:97]
	v_mfma_f32_16x16x32_bf16 v[90:93], v[158:161], v[208:211], v[90:93]
	v_mfma_f32_16x16x32_bf16 v[78:81], v[150:153], v[216:219], v[78:81]
	v_mfma_f32_16x16x32_bf16 v[74:77], v[158:161], v[216:219], v[74:77]
	s_setprio 0
	s_setprio 1
	v_mfma_f32_16x16x32_bf16 v[118:121], v[162:165], v[178:181], v[118:121]
	v_mfma_f32_16x16x32_bf16 v[114:117], v[170:173], v[178:181], v[114:117]
	v_mfma_f32_16x16x32_bf16 v[102:105], v[162:165], v[186:189], v[102:105]
	v_mfma_f32_16x16x32_bf16 v[98:101], v[170:173], v[186:189], v[98:101]
	v_mfma_f32_16x16x32_bf16 v[86:89], v[162:165], v[204:207], v[86:89]
	v_mfma_f32_16x16x32_bf16 v[82:85], v[170:173], v[204:207], v[82:85]
	v_mfma_f32_16x16x32_bf16 v[70:73], v[162:165], v[212:215], v[70:73]
	v_mfma_f32_16x16x32_bf16 v[66:69], v[170:173], v[212:215], v[66:69]
	v_mfma_f32_16x16x32_bf16 v[118:121], v[166:169], v[182:185], v[118:121]
	v_mfma_f32_16x16x32_bf16 v[114:117], v[174:177], v[182:185], v[114:117]
	v_mfma_f32_16x16x32_bf16 v[102:105], v[166:169], v[190:193], v[102:105]
	v_mfma_f32_16x16x32_bf16 v[98:101], v[174:177], v[190:193], v[98:101]
	v_mfma_f32_16x16x32_bf16 v[86:89], v[166:169], v[208:211], v[86:89]
	v_mfma_f32_16x16x32_bf16 v[82:85], v[174:177], v[208:211], v[82:85]
	v_mfma_f32_16x16x32_bf16 v[70:73], v[166:169], v[216:219], v[70:73]
	v_mfma_f32_16x16x32_bf16 v[66:69], v[174:177], v[216:219], v[66:69]
	s_setprio 0
	s_barrier
; #define PG8_STAGE(bufoff, gbase, voff) do { _Pragma("unroll") for (int _i = 0; _i < 2; ++_i) \
;         __builtin_amdgcn_global_load_lds((const unsigned*)((const char*)(gbase) + (voff)[_i]), (PG8_LAS unsigned*)(lds + (bufoff) + ldsw + _i * 8192), 16, 0, 0); } while (0)
; #define PG8_LDA(dst, b, h) do { _Pragma("unroll") for (int m = 0; m < 4; ++m) _Pragma("unroll") for (int k = 0; k < 2; ++k) dst[m][k] = *(const PG8_LAS bf16x8*)(lds + PG8_SA(b, h) + aoff + m * 2048 + k * 1024); } while (0)
; #define PG8_MMA(ai, bj, At, Bt) do { __builtin_amdgcn_s_setprio(1); _Pragma("unroll") for (int m = 0; m < 4; ++m) _Pragma("unroll") for (int n = 0; n < 2; ++n) _Pragma("unroll") for (int k = 0; k < 2; ++k) \
;         acc[ai][bj][m][n] = __builtin_amdgcn_mfma_f32_16x16x32_bf16(Bt[n][k], At[m][k], acc[ai][bj][m][n], 0, 0, 0); __builtin_amdgcn_s_setprio(0); } while (0)
; #define PG8_WAIT_V(n) asm volatile("s_waitcnt vmcnt(" #n ")" ::: "memory")
; #define PG8_WAIT_L(n) asm volatile("s_waitcnt lgkmcnt(" #n ")" ::: "memory")
; #define PG8_BAR __builtin_amdgcn_s_barrier()
; #define PG8_SCHED __builtin_amdgcn_sched_barrier(0)
; template <class Epi, class Sched, bool ALIGN_EPI = false, bool SP2 = false>
; __device__ __forceinline__ void gemm_phase(PG8_LAS unsigned char* lds, const Gemm g, const Sched& S, const Epi& E) {
;     ...
;         for (int t = 0; t < nt; t += 2) {
;     ...
;             PG8_LDA(At, 1, 1); PG8_STAGE(PG8_SB(1, 0), b3, voffB); PG8_STAGE(PG8_SB(1, 1), b3 + hstep, voffB); PG8_STAGE(PG8_SA(1, 0), a3, voffA);
;             PG8_WAIT_V(8); PG8_WAIT_L(0); PG8_BAR; PG8_MMA(1, 0, At, B0); PG8_MMA(1, 1, At, B1); PG8_BAR; PG8_SCHED;
	s_add_i32 s46, s64, s49
	v_lshl_add_u64 v[220:221], v[220:221], 0, s[8:9]
	s_mov_b32 m0, s46
	ds_read_b128 v[178:181], v144 offset:49152
	ds_read_b128 v[182:185], v144 offset:50176
	ds_read_b128 v[186:189], v144 offset:51200
	ds_read_b128 v[190:193], v144 offset:52224
	ds_read_b128 v[204:207], v144 offset:53248
	ds_read_b128 v[208:211], v144 offset:54272
	ds_read_b128 v[212:215], v144 offset:55296
	ds_read_b128 v[216:219], v144 offset:56320
	global_load_lds_dwordx4 v[220:221], off
	s_add_i32 m0, s46, 0x2000
	s_add_u32 s42, s42, 0x40080
	v_lshl_add_u64 v[220:221], v[222:223], 0, s[8:9]
	s_addc_u32 s43, s43, 0
	s_add_i32 s46, s65, s49
	global_load_lds_dwordx4 v[220:221], off
	v_lshl_add_u64 v[220:221], s[42:43], 0, v[134:135]
	s_mov_b32 m0, s46
	s_nop 0
	global_load_lds_dwordx4 v[220:221], off
	v_lshl_add_u64 v[220:221], s[42:43], 0, v[130:131]
	s_add_i32 m0, s46, 0x2000
	s_nop 0
	global_load_lds_dwordx4 v[220:221], off
	v_lshl_add_u64 v[220:221], v[224:225], 0, s[8:9]
	s_mov_b32 m0, s56
	s_nop 0
	global_load_lds_dwordx4 v[220:221], off
	v_lshl_add_u64 v[220:221], v[226:227], 0, s[8:9]
	s_mov_b32 m0, s57
	s_nop 0
	global_load_lds_dwordx4 v[220:221], off
	s_waitcnt vmcnt(8)
	s_waitcnt lgkmcnt(0)
	s_barrier
	s_setprio 1
	s_waitcnt lgkmcnt(0)
	v_mfma_f32_16x16x32_bf16 v[62:65], v[146:149], v[178:181], v[62:65]
	v_mfma_f32_16x16x32_bf16 v[58:61], v[154:157], v[178:181], v[58:61]
	v_mfma_f32_16x16x32_bf16 v[46:49], v[146:149], v[186:189], v[46:49]
	v_mfma_f32_16x16x32_bf16 v[42:45], v[154:157], v[186:189], v[42:45]
	v_mfma_f32_16x16x32_bf16 v[28:31], v[146:149], v[204:207], v[28:31]
	v_mfma_f32_16x16x32_bf16 v[24:27], v[154:157], v[204:207], v[24:27]
	v_mfma_f32_16x16x32_bf16 v[12:15], v[146:149], v[212:215], v[12:15]
	v_mfma_f32_16x16x32_bf16 v[8:11], v[154:157], v[212:215], v[8:11]
	v_mfma_f32_16x16x32_bf16 v[62:65], v[150:153], v[182:185], v[62:65]
	v_mfma_f32_16x16x32_bf16 v[58:61], v[158:161], v[182:185], v[58:61]
	v_mfma_f32_16x16x32_bf16 v[46:49], v[150:153], v[190:193], v[46:49]
	v_mfma_f32_16x16x32_bf16 v[42:45], v[158:161], v[190:193], v[42:45]
	v_mfma_f32_16x16x32_bf16 v[28:31], v[150:153], v[208:211], v[28:31]
	v_mfma_f32_16x16x32_bf16 v[24:27], v[158:161], v[208:211], v[24:27]
	v_mfma_f32_16x16x32_bf16 v[12:15], v[150:153], v[216:219], v[12:15]
	v_mfma_f32_16x16x32_bf16 v[8:11], v[158:161], v[216:219], v[8:11]
	s_setprio 0
	s_setprio 1
	v_mfma_f32_16x16x32_bf16 v[54:57], v[162:165], v[178:181], v[54:57]
	v_mfma_f32_16x16x32_bf16 v[50:53], v[170:173], v[178:181], v[50:53]
	v_mfma_f32_16x16x32_bf16 v[38:41], v[162:165], v[186:189], v[38:41]
	v_mfma_f32_16x16x32_bf16 v[34:37], v[170:173], v[186:189], v[34:37]
	v_mfma_f32_16x16x32_bf16 v[20:23], v[162:165], v[204:207], v[20:23]
	v_mfma_f32_16x16x32_bf16 v[16:19], v[170:173], v[204:207], v[16:19]
	v_mfma_f32_16x16x32_bf16 v[4:7], v[162:165], v[212:215], v[4:7]
	v_mfma_f32_16x16x32_bf16 v[0:3], v[170:173], v[212:215], v[0:3]
	v_mfma_f32_16x16x32_bf16 v[54:57], v[166:169], v[182:185], v[54:57]
	v_mfma_f32_16x16x32_bf16 v[50:53], v[174:177], v[182:185], v[50:53]
	v_mfma_f32_16x16x32_bf16 v[38:41], v[166:169], v[190:193], v[38:41]
	v_mfma_f32_16x16x32_bf16 v[34:37], v[174:177], v[190:193], v[34:37]
	v_mfma_f32_16x16x32_bf16 v[20:23], v[166:169], v[208:211], v[20:23]
	v_mfma_f32_16x16x32_bf16 v[16:19], v[174:177], v[208:211], v[16:19]
	v_mfma_f32_16x16x32_bf16 v[4:7], v[166:169], v[216:219], v[4:7]
	v_mfma_f32_16x16x32_bf16 v[0:3], v[174:177], v[216:219], v[0:3]
	s_setprio 0
	s_barrier
	s_add_i32 s63, s63, 2
	s_add_u32 s36, s36, 0x100
	s_addc_u32 s37, s37, 0
	s_add_u32 s61, s61, 0x100
	s_addc_u32 s62, s62, 0
	s_cmp_gt_u32 s63, 13
	s_cbranch_scc0 .LBB0_936
.Lgx3:
	s_and_b64 vcc, exec, s[22:23]
	s_cbranch_vccz .LBB0_939
	s_barrier
